# plus P3 pooling-GEMM epilogue: all z/scale loads hoisted and issued together instead of 16 serial load-wait round trips
# speedup vs baseline: 1.0627x; 1.0627x over previous
; #define LAS __attribute__((address_space(3)))
; #define GLDS_STAGE(st, kt_) do { \
;         _Pragma("unroll") for (int i_ = 0; i_ < FI; ++i_) { \
;             glds16(ap + (size_t)(32 * i_) * lda + (kt_) * 64, l3a + (st) + tid * 16 + i_ * 4096); \
;             glds16(bp + (size_t)(32 * i_) * ldb + (kt_) * 64, l3a + (st) + OPB + tid * 16 + i_ * 4096); } } while (0)
; #define GLDS_STAGE(st, kt_) do { \
;         _Pragma("unroll") for (int i_ = 0; i_ < 4; ++i_) { \
;             glds16(ap + (size_t)(64 * i_) * lda + (kt_) * 64, l3a + (st) + tid * 16 + i_ * 8192); \
;             glds16(bp + (size_t)(64 * i_) * ldb + (kt_) * 64, l3a + (st) + 32768 + tid * 16 + i_ * 8192); } } while (0)
; template <int WT, class Epi>
; DEV void gemm_tile(const bf16_t* __restrict__ A, int lda, const bf16_t* __restrict__ Bt, int ldb, int K, unsigned char* lds, const Epi& epi) {
;     ...
;     const int lrow = tid >> 3, lcs = (tid & 7) ^ (lrow & 7);
;     const bf16_t* ap = A + (size_t)lrow * lda + lcs * 8;
;     const bf16_t* bp = Bt + (size_t)lrow * ldb + lcs * 8;
;     const unsigned l3a = (unsigned)(size_t)(LAS unsigned char*)lds;
;     const int nk = K >> 6;
;     ...
;     constexpr int NSTG = 65536 / STB;
; #pragma unroll
;     for (int s_ = 0; s_ < NSTG - 1; ++s_) if (s_ < nk) GLDS_STAGE(s_ * STB, s_);
;     const int aoff = (wr * WT + fr) * 128, boff = OPB + (wc * WT + fr) * 128, sw = fr & 7;
;     int cur = 0, nxt = (NSTG - 1) * STB;
;     for (int kt = 0; kt < nk; ++kt) {
;         if (NSTG == 4 && kt + 2 < nk) { if (FI == 2) asm volatile("s_waitcnt vmcnt(8)" ::: "memory"); else asm volatile("s_waitcnt vmcnt(0)" ::: "memory"); }
;         else asm volatile("s_waitcnt vmcnt(0)" ::: "memory");
;         __syncthreads();
;         if (kt + NSTG - 1 < nk) GLDS_STAGE(nxt, kt + NSTG - 1);
; __global__ void __launch_bounds__(512) hymba_fwd(Params p) {
;     ...
;             for (int t0 = 2 * ob; t0 < NPL; t0 += 2 * no) { const int t = min(t0 + vb, NPL - 1); int nt, mt; tile_map(t, 68, 8, mt, nt); const int g = nt >> 1;
;                 EpiPoolS e{mt * 128, nt * 128, proj, p.in[15], mix + (size_t)mt * 128 * LDB + 1024 + nt * 128, LDB};
;                 gemm_tile<64>(dpl + (size_t)mt * 128 * LDP + g * 256, LDP, Wt_pool + (size_t)nt * 128 * LDM, LDM, 256, vlds, e);
.LBB0_870:
	s_add_i32 s14, s71, s72
	s_min_i32 s14, s14, 0x21f
	s_and_b32 s15, s14, 7
	s_mulk_i32 s15, 0x44
	s_ashr_i32 s14, s14, 3
	s_add_i32 s14, s15, s14
	s_ashr_i32 s15, s14, 31
	s_lshr_b32 s15, s15, 26
	s_add_i32 s15, s14, s15
	s_ashr_i32 s68, s15, 6
	s_lshl_b32 s81, s68, 3
	s_sub_i32 s68, 0x44, s81
	s_andn2_b32 s15, s15, 63
	s_min_u32 s82, s68, 8
	s_sub_i32 s14, s14, s15
	s_sext_i32_i8 s15, s14
	v_cvt_f32_ubyte0_e32 v3, s82
	v_cvt_f32_i32_e32 v2, s15
	v_rcp_iflag_f32_e32 v4, v3
	s_ashr_i32 s68, s15, 30
	s_or_b32 s83, s68, 1
	v_mov_b32_e32 v137, v1
	v_mul_f32_e32 v4, v2, v4
	v_trunc_f32_e32 v4, v4
	v_fma_f32 v2, -v4, v3, v2
	v_cvt_i32_f32_e32 v4, v4
	v_cmp_ge_f32_e64 s[68:69], |v2|, v3
	s_and_b64 s[68:69], s[68:69], exec
	s_cselect_b32 s15, s83, 0
	v_readfirstlane_b32 s68, v4
	s_add_i32 s15, s68, s15
	s_sext_i32_i8 s84, s15
	s_mul_i32 s15, s15, s82
	s_sub_i32 s14, s14, s15
	s_sext_i32_i8 s14, s14
	s_add_i32 s14, s81, s14
	s_lshl_b32 s68, s84, 7
	v_mad_i64_i32 v[2:3], s[82:83], s14, v134, v[174:175]
	s_ashr_i32 s69, s68, 31
	v_lshl_add_u64 v[132:133], s[68:69], 1, v[2:3]
	v_mad_i64_i32 v[2:3], s[82:83], s14, v135, v[140:141]
	s_and_b32 s82, s68, 0xffffff00
	s_ashr_i32 s83, s82, 31
	v_ashrrev_i32_e32 v6, 3, v137
	v_xor_b32_e32 v7, v6, v137
	v_lshl_add_u64 v[2:3], s[82:83], 1, v[2:3]
	v_mad_i64_i32 v[4:5], s[82:83], s84, v136, v[138:139]
	v_lshlrev_b32_e32 v7, 4, v7
	v_lshlrev_b32_e32 v9, 4, v137
	v_mad_i64_i32 v[2:3], s[82:83], v6, s77, v[2:3]
	v_and_b32_e32 v130, 0x70, v7
	v_mad_i64_i32 v[4:5], s[82:83], v6, s78, v[4:5]
	v_add_u32_e32 v6, s70, v9
	s_lshl_b32 s81, s14, 7
	v_lshl_add_u64 v[2:3], v[2:3], 0, v[130:131]
	v_add_u32_e32 v7, 0x4000, v6
	v_readfirstlane_b32 s14, v6
	s_mov_b32 s15, m0
	s_mov_b32 m0, s14
	s_nop 0
	global_load_lds_dwordx4 v[2:3], off
	s_mov_b32 m0, s15
	v_lshl_add_u64 v[4:5], v[4:5], 0, v[130:131]
	v_readfirstlane_b32 s15, v7
	s_mov_b32 s82, m0
	s_mov_b32 m0, s15
	s_nop 0
	global_load_lds_dwordx4 v[4:5], off
	s_mov_b32 m0, s82
	v_lshl_add_u64 v[6:7], v[2:3], 0, s[6:7]
	s_add_i32 s82, s14, 0x1000
	s_mov_b32 s83, m0
	s_mov_b32 m0, s82
	s_nop 0
	global_load_lds_dwordx4 v[6:7], off
	s_mov_b32 m0, s83
	v_lshl_add_u64 v[6:7], v[4:5], 0, s[8:9]
	s_add_i32 s83, s15, 0x1000
	s_mov_b32 s84, m0
	s_mov_b32 m0, s83
	s_nop 0
	global_load_lds_dwordx4 v[6:7], off
	s_mov_b32 m0, s84
	v_lshl_add_u64 v[6:7], v[2:3], 0, s[10:11]
	s_add_i32 s83, s14, 0x2000
	s_mov_b32 s84, m0
	s_mov_b32 m0, s83
	s_nop 0
	global_load_lds_dwordx4 v[6:7], off
	s_mov_b32 m0, s84
	v_lshl_add_u64 v[6:7], v[4:5], 0, s[12:13]
	s_add_i32 s84, s15, 0x2000
	s_mov_b32 s85, m0
	s_mov_b32 m0, s84
	s_nop 0
	global_load_lds_dwordx4 v[6:7], off
	s_mov_b32 m0, s85
	v_lshl_add_u64 v[6:7], v[2:3], 0, s[16:17]
	s_add_i32 s84, s14, 0x3000
	s_mov_b32 s85, m0
	s_mov_b32 m0, s84
	s_nop 0
	global_load_lds_dwordx4 v[6:7], off
	s_mov_b32 m0, s85
	v_lshl_add_u64 v[6:7], v[4:5], 0, s[18:19]
	v_and_b32_e32 v8, 15, v137
	s_addk_i32 s15, 0x3000
	s_mov_b32 s85, m0
	s_mov_b32 m0, s15
	s_nop 0
	global_load_lds_dwordx4 v[6:7], off
	s_mov_b32 m0, s85
	v_ashrrev_i32_e32 v6, 1, v137
	v_and_or_b32 v130, v6, s76, v8
	v_lshlrev_b32_e32 v6, 7, v137
	v_add_u32_e32 v102, 0x4000, v9
	v_add_u32_e32 v12, s73, v9
	v_and_b32_e32 v11, 0x2780, v6
	s_waitcnt vmcnt(0)
	s_waitcnt lgkmcnt(0)
	s_barrier
	v_lshl_add_u64 v[6:7], v[2:3], 0, s[20:21]
	v_add_u32_e32 v13, s73, v102
	v_readfirstlane_b32 s15, v12
	s_mov_b32 s85, m0
	s_mov_b32 m0, s15
	s_nop 0
	global_load_lds_dwordx4 v[6:7], off
	s_mov_b32 m0, s85
	v_lshl_add_u64 v[8:9], v[4:5], 0, s[20:21]
	v_readfirstlane_b32 s85, v13
	s_mov_b32 s86, m0
	s_mov_b32 m0, s85
	s_nop 0
	global_load_lds_dwordx4 v[8:9], off
	s_mov_b32 m0, s86
	v_lshl_add_u64 v[6:7], v[2:3], 0, s[22:23]
	s_add_i32 s86, s15, 0x1000
	s_mov_b32 s87, m0
	s_mov_b32 m0, s86
	s_nop 0
	global_load_lds_dwordx4 v[6:7], off
	s_mov_b32 m0, s87
	v_lshl_add_u64 v[6:7], v[4:5], 0, s[24:25]
	s_add_i32 s87, s85, 0x1000
	s_mov_b32 s88, m0
	s_mov_b32 m0, s87
	s_nop 0
	global_load_lds_dwordx4 v[6:7], off
	s_mov_b32 m0, s88
	v_lshl_add_u64 v[6:7], v[2:3], 0, s[26:27]
	s_add_i32 s88, s15, 0x2000
	s_mov_b32 s89, m0
	s_mov_b32 m0, s88
	s_nop 0
	global_load_lds_dwordx4 v[6:7], off
	s_mov_b32 m0, s89
	v_lshl_add_u64 v[6:7], v[4:5], 0, s[30:31]
	s_add_i32 s89, s85, 0x2000
	s_mov_b32 s90, m0
	s_mov_b32 m0, s89
	s_nop 0
	global_load_lds_dwordx4 v[6:7], off
	s_mov_b32 m0, s90
	v_lshl_add_u64 v[6:7], v[2:3], 0, s[34:35]
	v_lshrrev_b32_e32 v10, 4, v137
	v_and_b32_e32 v74, 7, v137
	s_add_i32 s90, s15, 0x3000
	s_mov_b32 s91, m0
	s_mov_b32 m0, s90
	s_nop 0
	global_load_lds_dwordx4 v[6:7], off
	s_mov_b32 m0, s91
	v_lshl_add_u64 v[6:7], v[4:5], 0, s[36:37]
	s_add_i32 s91, s85, 0x3000
	s_mov_b32 s92, m0
	s_mov_b32 m0, s91
	s_nop 0
	global_load_lds_dwordx4 v[6:7], off
	s_mov_b32 m0, s92
	v_bitop3_b32 v6, v10, v74, 3 bitop3:0x6c
	v_lshl_add_u32 v75, v130, 7, s70
	v_lshlrev_b32_e32 v6, 4, v6
	v_add_u32_e32 v76, s70, v11
	v_add_u32_e32 v126, v75, v6
	v_add_u32_e32 v118, v76, v6
	ds_read_b128 v[6:9], v126
	ds_read_b128 v[10:13], v118 offset:16384
	ds_read_b128 v[14:17], v126 offset:2048
	ds_read_b128 v[18:21], v118 offset:18432
	ds_read_b128 v[22:25], v126 offset:4096
	ds_read_b128 v[26:29], v118 offset:20480
	ds_read_b128 v[30:33], v126 offset:6144
	ds_read_b128 v[34:37], v118 offset:22528
	v_bfe_u32 v142, v137, 4, 2
	s_waitcnt lgkmcnt(6)
	v_mfma_f32_16x16x32_bf16 v[38:41], v[10:13], v[6:9], 0
	v_and_b32_e32 v143, 64, v137
	s_add_i32 s72, s72, s74
	s_waitcnt lgkmcnt(4)
	v_mfma_f32_16x16x32_bf16 v[42:45], v[18:21], v[6:9], 0
	s_waitcnt lgkmcnt(2)
	v_mfma_f32_16x16x32_bf16 v[46:49], v[26:29], v[6:9], 0
	s_waitcnt lgkmcnt(0)
	v_mfma_f32_16x16x32_bf16 v[6:9], v[34:37], v[6:9], 0
	v_mfma_f32_16x16x32_bf16 v[50:53], v[10:13], v[14:17], 0
	v_mfma_f32_16x16x32_bf16 v[54:57], v[18:21], v[14:17], 0
	v_mfma_f32_16x16x32_bf16 v[58:61], v[26:29], v[14:17], 0
	v_mfma_f32_16x16x32_bf16 v[14:17], v[34:37], v[14:17], 0
	v_mfma_f32_16x16x32_bf16 v[62:65], v[10:13], v[22:25], 0
	v_mfma_f32_16x16x32_bf16 v[66:69], v[18:21], v[22:25], 0
	v_mfma_f32_16x16x32_bf16 v[70:73], v[26:29], v[22:25], 0
	v_mfma_f32_16x16x32_bf16 v[22:25], v[34:37], v[22:25], 0
	v_mfma_f32_16x16x32_bf16 v[10:13], v[10:13], v[30:33], 0
	v_mfma_f32_16x16x32_bf16 v[18:21], v[18:21], v[30:33], 0
	v_mfma_f32_16x16x32_bf16 v[26:29], v[26:29], v[30:33], 0
	v_mfma_f32_16x16x32_bf16 v[30:33], v[34:37], v[30:33], 0
	v_bitop3_b32 v34, v142, v74, 4 bitop3:0x36
	v_lshlrev_b32_e32 v34, 4, v34
	v_add_u32_e32 v114, v75, v34
	v_add_u32_e32 v115, v76, v34
	ds_read_b128 v[34:37], v114
	ds_read_b128 v[74:77], v115 offset:16384
	ds_read_b128 v[78:81], v114 offset:2048
	ds_read_b128 v[82:85], v115 offset:18432
	ds_read_b128 v[86:89], v114 offset:4096
	ds_read_b128 v[90:93], v115 offset:20480
	ds_read_b128 v[94:97], v114 offset:6144
	ds_read_b128 v[98:101], v115 offset:22528
	s_waitcnt lgkmcnt(6)
	v_mfma_f32_16x16x32_bf16 v[38:41], v[74:77], v[34:37], v[38:41]
	s_waitcnt vmcnt(0)
	s_waitcnt lgkmcnt(0)
	s_barrier
; #define GLDS_STAGE(st, kt_) do { \
;         _Pragma("unroll") for (int i_ = 0; i_ < FI; ++i_) { \
;             glds16(ap + (size_t)(32 * i_) * lda + (kt_) * 64, l3a + (st) + tid * 16 + i_ * 4096); \
;             glds16(bp + (size_t)(32 * i_) * ldb + (kt_) * 64, l3a + (st) + OPB + tid * 16 + i_ * 4096); } } while (0)
; #define GLDS_STAGE(st, kt_) do { \
;         _Pragma("unroll") for (int i_ = 0; i_ < 4; ++i_) { \
;             glds16(ap + (size_t)(64 * i_) * lda + (kt_) * 64, l3a + (st) + tid * 16 + i_ * 8192); \
;             glds16(bp + (size_t)(64 * i_) * ldb + (kt_) * 64, l3a + (st) + 32768 + tid * 16 + i_ * 8192); } } while (0)
; template <int WT, class Epi>
; DEV void gemm_tile(const bf16_t* __restrict__ A, int lda, const bf16_t* __restrict__ Bt, int ldb, int K, unsigned char* lds, const Epi& epi) {
;     ...
;     for (int kt = 0; kt < nk; ++kt) {
;         if (NSTG == 4 && kt + 2 < nk) { if (FI == 2) asm volatile("s_waitcnt vmcnt(8)" ::: "memory"); else asm volatile("s_waitcnt vmcnt(0)" ::: "memory"); }
;         else asm volatile("s_waitcnt vmcnt(0)" ::: "memory");
;         __syncthreads();
;         if (kt + NSTG - 1 < nk) GLDS_STAGE(nxt, kt + NSTG - 1);
; #pragma unroll
;         for (int kh = 0; kh < 2; ++kh) {
;             bf16x8 af[FI], bfr[FI];
;             const int ch = ((kh * 4 + fq) ^ sw) << 4;
; #pragma unroll
;             for (int i = 0; i < FI; ++i) { af[i] = *(const bf16x8*)(lds + cur + aoff + i * 2048 + ch); bfr[i] = *(const bf16x8*)(lds + cur + boff + i * 2048 + ch); }
; #pragma unroll
;             for (int mi = 0; mi < FI; ++mi)
; #pragma unroll
;                 for (int ni = 0; ni < FI; ++ni) acc[mi][ni] = __builtin_amdgcn_mfma_f32_16x16x32_bf16(bfr[ni], af[mi], acc[mi][ni], 0, 0, 0);
;         }
;         nxt = cur; cur += STB; if (cur == NSTG * STB) cur = 0;
	v_mfma_f32_16x16x32_bf16 v[42:45], v[82:85], v[34:37], v[42:45]
	v_mfma_f32_16x16x32_bf16 v[46:49], v[90:93], v[34:37], v[46:49]
	v_mfma_f32_16x16x32_bf16 v[6:9], v[98:101], v[34:37], v[6:9]
	v_mfma_f32_16x16x32_bf16 v[34:37], v[74:77], v[78:81], v[50:53]
	v_mfma_f32_16x16x32_bf16 v[50:53], v[82:85], v[78:81], v[54:57]
	v_mfma_f32_16x16x32_bf16 v[54:57], v[90:93], v[78:81], v[58:61]
	v_mfma_f32_16x16x32_bf16 v[58:61], v[74:77], v[86:89], v[62:65]
	v_mfma_f32_16x16x32_bf16 v[62:65], v[82:85], v[86:89], v[66:69]
	v_mfma_f32_16x16x32_bf16 v[66:69], v[90:93], v[86:89], v[70:73]
	v_mfma_f32_16x16x32_bf16 v[10:13], v[74:77], v[94:97], v[10:13]
	s_nop 1
	v_lshl_add_u64 v[70:71], v[2:3], 0, s[38:39]
	v_add_u32_e32 v74, s70, v102
	s_mov_b32 s92, m0
	s_mov_b32 m0, s14
	s_nop 0
	global_load_lds_dwordx4 v[70:71], off
	s_mov_b32 m0, s92
	v_lshl_add_u64 v[72:73], v[4:5], 0, s[38:39]
	v_readfirstlane_b32 s14, v74
	s_mov_b32 s92, m0
	s_mov_b32 m0, s14
	s_nop 0
	global_load_lds_dwordx4 v[72:73], off
	s_mov_b32 m0, s92
	v_lshl_add_u64 v[70:71], v[2:3], 0, s[40:41]
	s_mov_b32 s92, m0
	s_mov_b32 m0, s82
	s_nop 0
	global_load_lds_dwordx4 v[70:71], off
	s_mov_b32 m0, s92
	v_lshl_add_u64 v[70:71], v[4:5], 0, s[42:43]
	s_add_i32 s82, s14, 0x1000
	s_mov_b32 s92, m0
	s_mov_b32 m0, s82
	s_nop 0
	global_load_lds_dwordx4 v[70:71], off
	s_mov_b32 m0, s92
	v_lshl_add_u64 v[70:71], v[2:3], 0, s[44:45]
	s_mov_b32 s82, m0
	s_mov_b32 m0, s83
	s_nop 0
	global_load_lds_dwordx4 v[70:71], off
	s_mov_b32 m0, s82
	v_lshl_add_u64 v[70:71], v[4:5], 0, s[46:47]
	s_add_i32 s82, s14, 0x2000
	s_mov_b32 s83, m0
	s_mov_b32 m0, s82
	s_nop 0
	global_load_lds_dwordx4 v[70:71], off
	s_mov_b32 m0, s83
	v_lshl_add_u64 v[70:71], v[2:3], 0, s[48:49]
	s_mov_b32 s82, m0
	s_mov_b32 m0, s84
	s_nop 0
	global_load_lds_dwordx4 v[70:71], off
	s_mov_b32 m0, s82
	v_lshl_add_u64 v[70:71], v[4:5], 0, s[50:51]
	s_addk_i32 s14, 0x3000
	s_mov_b32 s82, m0
	s_mov_b32 m0, s14
	s_nop 0
	global_load_lds_dwordx4 v[70:71], off
	s_mov_b32 m0, s82
	v_mfma_f32_16x16x32_bf16 v[14:17], v[98:101], v[78:81], v[14:17]
	s_cmpk_lt_i32 s72, 0x220
	v_mfma_f32_16x16x32_bf16 v[22:25], v[98:101], v[86:89], v[22:25]
	v_mfma_f32_16x16x32_bf16 v[18:21], v[82:85], v[94:97], v[18:21]
	v_mfma_f32_16x16x32_bf16 v[26:29], v[90:93], v[94:97], v[26:29]
	v_mfma_f32_16x16x32_bf16 v[30:33], v[98:101], v[94:97], v[30:33]
	ds_read_b128 v[70:73], v126 offset:32768
	ds_read_b128 v[74:77], v118 offset:49152
	ds_read_b128 v[78:81], v126 offset:34816
	ds_read_b128 v[82:85], v118 offset:51200
	ds_read_b128 v[86:89], v126 offset:36864
	ds_read_b128 v[90:93], v118 offset:53248
	ds_read_b128 v[94:97], v126 offset:38912
	ds_read_b128 v[98:101], v118 offset:55296
	s_waitcnt lgkmcnt(6)
	v_mfma_f32_16x16x32_bf16 v[38:41], v[74:77], v[70:73], v[38:41]
	s_waitcnt lgkmcnt(4)
	v_mfma_f32_16x16x32_bf16 v[42:45], v[82:85], v[70:73], v[42:45]
	s_waitcnt lgkmcnt(2)
	v_mfma_f32_16x16x32_bf16 v[46:49], v[90:93], v[70:73], v[46:49]
	s_waitcnt lgkmcnt(0)
	v_mfma_f32_16x16x32_bf16 v[6:9], v[98:101], v[70:73], v[6:9]
	v_mfma_f32_16x16x32_bf16 v[34:37], v[74:77], v[78:81], v[34:37]
	v_mfma_f32_16x16x32_bf16 v[50:53], v[82:85], v[78:81], v[50:53]
	v_mfma_f32_16x16x32_bf16 v[54:57], v[90:93], v[78:81], v[54:57]
	v_mfma_f32_16x16x32_bf16 v[14:17], v[98:101], v[78:81], v[14:17]
	v_mfma_f32_16x16x32_bf16 v[58:61], v[74:77], v[86:89], v[58:61]
	v_mfma_f32_16x16x32_bf16 v[62:65], v[82:85], v[86:89], v[62:65]
	v_mfma_f32_16x16x32_bf16 v[66:69], v[90:93], v[86:89], v[66:69]
	v_mfma_f32_16x16x32_bf16 v[22:25], v[98:101], v[86:89], v[22:25]
	v_mfma_f32_16x16x32_bf16 v[10:13], v[74:77], v[94:97], v[10:13]
	v_mfma_f32_16x16x32_bf16 v[18:21], v[82:85], v[94:97], v[18:21]
	v_mfma_f32_16x16x32_bf16 v[26:29], v[90:93], v[94:97], v[26:29]
	v_mfma_f32_16x16x32_bf16 v[30:33], v[98:101], v[94:97], v[30:33]
	ds_read_b128 v[70:73], v114 offset:32768
	ds_read_b128 v[74:77], v115 offset:49152
	ds_read_b128 v[78:81], v114 offset:34816
	ds_read_b128 v[82:85], v115 offset:51200
	ds_read_b128 v[86:89], v114 offset:36864
	ds_read_b128 v[90:93], v115 offset:53248
	ds_read_b128 v[94:97], v114 offset:38912
	ds_read_b128 v[98:101], v115 offset:55296
	s_waitcnt vmcnt(0)
	s_waitcnt lgkmcnt(0)
	v_mfma_f32_16x16x32_bf16 v[38:41], v[74:77], v[70:73], v[38:41]
	s_barrier
; #define GLDS_STAGE(st, kt_) do { \
;         _Pragma("unroll") for (int i_ = 0; i_ < FI; ++i_) { \
;             glds16(ap + (size_t)(32 * i_) * lda + (kt_) * 64, l3a + (st) + tid * 16 + i_ * 4096); \
;             glds16(bp + (size_t)(32 * i_) * ldb + (kt_) * 64, l3a + (st) + OPB + tid * 16 + i_ * 4096); } } while (0)
; #define GLDS_STAGE(st, kt_) do { \
;         _Pragma("unroll") for (int i_ = 0; i_ < 4; ++i_) { \
;             glds16(ap + (size_t)(64 * i_) * lda + (kt_) * 64, l3a + (st) + tid * 16 + i_ * 8192); \
;             glds16(bp + (size_t)(64 * i_) * ldb + (kt_) * 64, l3a + (st) + 32768 + tid * 16 + i_ * 8192); } } while (0)
; template <int WT, class Epi>
; DEV void gemm_tile(const bf16_t* __restrict__ A, int lda, const bf16_t* __restrict__ Bt, int ldb, int K, unsigned char* lds, const Epi& epi) {
;     ...
;     for (int kt = 0; kt < nk; ++kt) {
;         if (NSTG == 4 && kt + 2 < nk) { if (FI == 2) asm volatile("s_waitcnt vmcnt(8)" ::: "memory"); else asm volatile("s_waitcnt vmcnt(0)" ::: "memory"); }
;         else asm volatile("s_waitcnt vmcnt(0)" ::: "memory");
;         __syncthreads();
;         if (kt + NSTG - 1 < nk) GLDS_STAGE(nxt, kt + NSTG - 1);
; #pragma unroll
;         for (int kh = 0; kh < 2; ++kh) {
;             bf16x8 af[FI], bfr[FI];
;             const int ch = ((kh * 4 + fq) ^ sw) << 4;
; #pragma unroll
;             for (int i = 0; i < FI; ++i) { af[i] = *(const bf16x8*)(lds + cur + aoff + i * 2048 + ch); bfr[i] = *(const bf16x8*)(lds + cur + boff + i * 2048 + ch); }
; #pragma unroll
;             for (int mi = 0; mi < FI; ++mi)
; #pragma unroll
;                 for (int ni = 0; ni < FI; ++ni) acc[mi][ni] = __builtin_amdgcn_mfma_f32_16x16x32_bf16(bfr[ni], af[mi], acc[mi][ni], 0, 0, 0);
;         }
;         nxt = cur; cur += STB; if (cur == NSTG * STB) cur = 0;
;     }
;     ...
;     __syncthreads();
	v_mfma_f32_16x16x32_bf16 v[42:45], v[82:85], v[70:73], v[42:45]
	v_mfma_f32_16x16x32_bf16 v[46:49], v[90:93], v[70:73], v[46:49]
	v_mfma_f32_16x16x32_bf16 v[6:9], v[98:101], v[70:73], v[6:9]
	v_lshl_add_u64 v[70:71], v[2:3], 0, s[52:53]
	s_mov_b32 s14, m0
	s_mov_b32 m0, s15
	s_nop 0
	global_load_lds_dwordx4 v[70:71], off
	s_mov_b32 m0, s14
	v_lshl_add_u64 v[72:73], v[4:5], 0, s[52:53]
	s_mov_b32 s14, m0
	s_mov_b32 m0, s85
	s_nop 0
	global_load_lds_dwordx4 v[72:73], off
	s_mov_b32 m0, s14
	v_lshl_add_u64 v[70:71], v[2:3], 0, s[54:55]
	s_mov_b32 s14, m0
	s_mov_b32 m0, s86
	s_nop 0
	global_load_lds_dwordx4 v[70:71], off
	s_mov_b32 m0, s14
	v_lshl_add_u64 v[70:71], v[4:5], 0, s[56:57]
	s_mov_b32 s14, m0
	s_mov_b32 m0, s87
	s_nop 0
	global_load_lds_dwordx4 v[70:71], off
	s_mov_b32 m0, s14
	v_lshl_add_u64 v[70:71], v[2:3], 0, s[58:59]
	s_mov_b32 s14, m0
	s_mov_b32 m0, s88
	s_nop 0
	global_load_lds_dwordx4 v[70:71], off
	s_mov_b32 m0, s14
	v_lshl_add_u64 v[70:71], v[4:5], 0, s[60:61]
	s_mov_b32 s14, m0
	s_mov_b32 m0, s89
	s_nop 0
	global_load_lds_dwordx4 v[70:71], off
	s_mov_b32 m0, s14
	v_lshl_add_u64 v[2:3], v[2:3], 0, s[62:63]
	s_mov_b32 s14, m0
	s_mov_b32 m0, s90
	s_nop 0
	global_load_lds_dwordx4 v[2:3], off
	s_mov_b32 m0, s14
	v_lshl_add_u64 v[2:3], v[4:5], 0, s[64:65]
	s_mov_b32 s14, m0
	s_mov_b32 m0, s91
	s_nop 0
	global_load_lds_dwordx4 v[2:3], off
	s_mov_b32 m0, s14
	v_mfma_f32_16x16x32_bf16 v[34:37], v[74:77], v[78:81], v[34:37]
	v_mfma_f32_16x16x32_bf16 v[50:53], v[82:85], v[78:81], v[50:53]
	v_mfma_f32_16x16x32_bf16 v[54:57], v[90:93], v[78:81], v[54:57]
	v_mfma_f32_16x16x32_bf16 v[14:17], v[98:101], v[78:81], v[14:17]
	v_mfma_f32_16x16x32_bf16 v[58:61], v[74:77], v[86:89], v[58:61]
	v_mfma_f32_16x16x32_bf16 v[62:65], v[82:85], v[86:89], v[62:65]
	v_mfma_f32_16x16x32_bf16 v[66:69], v[90:93], v[86:89], v[66:69]
	v_mfma_f32_16x16x32_bf16 v[22:25], v[98:101], v[86:89], v[22:25]
	v_mfma_f32_16x16x32_bf16 v[10:13], v[74:77], v[94:97], v[10:13]
	v_mfma_f32_16x16x32_bf16 v[18:21], v[82:85], v[94:97], v[18:21]
	v_mfma_f32_16x16x32_bf16 v[26:29], v[90:93], v[94:97], v[26:29]
	v_mfma_f32_16x16x32_bf16 v[30:33], v[98:101], v[94:97], v[30:33]
	ds_read_b128 v[2:5], v126
	ds_read_b128 v[70:73], v118 offset:16384
	ds_read_b128 v[74:77], v126 offset:2048
	ds_read_b128 v[78:81], v118 offset:18432
	ds_read_b128 v[82:85], v126 offset:4096
	ds_read_b128 v[86:89], v118 offset:20480
	ds_read_b128 v[90:93], v126 offset:6144
	ds_read_b128 v[94:97], v118 offset:22528
	s_waitcnt lgkmcnt(6)
	v_mfma_f32_16x16x32_bf16 v[38:41], v[70:73], v[2:5], v[38:41]
	s_waitcnt lgkmcnt(4)
	v_mfma_f32_16x16x32_bf16 v[42:45], v[78:81], v[2:5], v[42:45]
	s_waitcnt lgkmcnt(2)
	v_mfma_f32_16x16x32_bf16 v[46:49], v[86:89], v[2:5], v[46:49]
	s_waitcnt lgkmcnt(0)
	v_mfma_f32_16x16x32_bf16 v[2:5], v[94:97], v[2:5], v[6:9]
	v_mfma_f32_16x16x32_bf16 v[6:9], v[70:73], v[74:77], v[34:37]
	v_mfma_f32_16x16x32_bf16 v[50:53], v[78:81], v[74:77], v[50:53]
	v_mfma_f32_16x16x32_bf16 v[54:57], v[86:89], v[74:77], v[54:57]
	v_mfma_f32_16x16x32_bf16 v[14:17], v[94:97], v[74:77], v[14:17]
	v_mfma_f32_16x16x32_bf16 v[58:61], v[70:73], v[82:85], v[58:61]
	v_mfma_f32_16x16x32_bf16 v[62:65], v[78:81], v[82:85], v[62:65]
	v_mfma_f32_16x16x32_bf16 v[66:69], v[86:89], v[82:85], v[66:69]
	v_mfma_f32_16x16x32_bf16 v[74:77], v[94:97], v[82:85], v[22:25]
	v_mfma_f32_16x16x32_bf16 v[10:13], v[70:73], v[90:93], v[10:13]
	v_mfma_f32_16x16x32_bf16 v[78:81], v[78:81], v[90:93], v[18:21]
	v_mfma_f32_16x16x32_bf16 v[82:85], v[86:89], v[90:93], v[26:29]
	v_mfma_f32_16x16x32_bf16 v[86:89], v[94:97], v[90:93], v[30:33]
	s_nop 2
	ds_read_b128 v[30:33], v114
	ds_read_b128 v[90:93], v115 offset:16384
	ds_read_b128 v[70:73], v114 offset:2048
	ds_read_b128 v[94:97], v115 offset:18432
	ds_read_b128 v[98:101], v114 offset:4096
	ds_read_b128 v[102:105], v115 offset:20480
	ds_read_b128 v[106:109], v114 offset:6144
	ds_read_b128 v[110:113], v115 offset:22528
	s_waitcnt vmcnt(0)
	s_waitcnt lgkmcnt(0)
	v_mfma_f32_16x16x32_bf16 v[18:21], v[90:93], v[30:33], v[38:41]
	s_barrier
	v_mfma_f32_16x16x32_bf16 v[22:25], v[94:97], v[30:33], v[42:45]
	v_mfma_f32_16x16x32_bf16 v[26:29], v[102:105], v[30:33], v[46:49]
	v_mfma_f32_16x16x32_bf16 v[30:33], v[110:113], v[30:33], v[2:5]
	v_mfma_f32_16x16x32_bf16 v[34:37], v[90:93], v[70:73], v[6:9]
	v_mfma_f32_16x16x32_bf16 v[38:41], v[94:97], v[70:73], v[50:53]
	v_mfma_f32_16x16x32_bf16 v[50:53], v[102:105], v[70:73], v[54:57]
	v_mfma_f32_16x16x32_bf16 v[54:57], v[110:113], v[70:73], v[14:17]
	v_mfma_f32_16x16x32_bf16 v[58:61], v[90:93], v[98:101], v[58:61]
	v_mfma_f32_16x16x32_bf16 v[62:65], v[94:97], v[98:101], v[62:65]
	v_mfma_f32_16x16x32_bf16 v[66:69], v[102:105], v[98:101], v[66:69]
	v_mfma_f32_16x16x32_bf16 v[70:73], v[110:113], v[98:101], v[74:77]
	v_mfma_f32_16x16x32_bf16 v[74:77], v[90:93], v[106:109], v[10:13]
	v_mfma_f32_16x16x32_bf16 v[78:81], v[94:97], v[106:109], v[78:81]
	v_mfma_f32_16x16x32_bf16 v[82:85], v[102:105], v[106:109], v[82:85]
	v_mfma_f32_16x16x32_bf16 v[86:89], v[110:113], v[106:109], v[86:89]
	ds_read_b128 v[2:5], v115 offset:55296
	ds_read_b128 v[42:45], v114 offset:38912
	ds_read_b128 v[6:9], v115 offset:53248
	ds_read_b128 v[14:17], v114 offset:36864
	ds_read_b128 v[10:13], v115 offset:51200
	ds_read_b128 v[90:93], v114 offset:34816
	ds_read_b128 v[46:49], v115 offset:49152
	ds_read_b128 v[94:97], v114 offset:32768
	ds_read_b128 v[98:101], v118 offset:55296
	ds_read_b128 v[102:105], v126 offset:38912
	ds_read_b128 v[106:109], v118 offset:53248
	ds_read_b128 v[114:117], v126 offset:36864
	ds_read_b128 v[110:113], v118 offset:51200
	ds_read_b128 v[122:125], v126 offset:34816
	ds_read_b128 v[118:121], v118 offset:49152
	ds_read_b128 v[126:129], v126 offset:32768
	s_waitcnt lgkmcnt(0)
	s_barrier
;     DEV f32x4 xform(int r, int c, f32x4 v) const {
;         const int row = m0 + r, col = n0 + c;
;         const uint2 z = *(const uint2*)(proj + (size_t)row * NPJ + C_ZB + col);
;         const f32x4 s = *(const f32x4*)(scale + col);
	v_lshl_or_b32 v184, v142, 2, v143
	v_add_u32_e32 v176, s81, v130
	v_or_b32_e32 v178, s68, v184
	v_mad_i64_i32 v[176:177], s[96:97], v176, s79, v[172:173]
	v_ashrrev_i32_e32 v179, 31, v178
	v_lshl_add_u64 v[182:183], v[176:177], 0, s[66:67]
	v_lshlrev_b64 v[180:181], 1, v[178:179]
	v_lshl_add_u64 v[176:177], v[182:183], 0, v[180:181]
	global_load_dwordx2 v[192:193], v[176:177], off
	v_lshl_or_b32 v180, v142, 2, v143
	v_or_b32_e32 v176, s68, v180
	v_ashrrev_i32_e32 v177, 31, v176
	v_lshl_add_u64 v[178:179], v[176:177], 2, s[4:5]
	global_load_dwordx4 v[194:197], v[178:179], off
	v_lshl_or_b32 v186, v142, 2, v143
	v_add_u32_e32 v176, s81, v130
	v_mad_i64_i32 v[176:177], s[96:97], v176, s79, v[172:173]
	v_lshl_add_u64 v[184:185], v[176:177], 0, s[66:67]
	v_or_b32_e32 v183, 16, v186
	v_or_b32_e32 v178, s68, v183
	v_ashrrev_i32_e32 v179, 31, v178
	v_lshlrev_b64 v[180:181], 1, v[178:179]
	v_lshl_add_u64 v[178:179], v[184:185], 0, v[180:181]
	global_load_dwordx2 v[198:199], v[178:179], off
	v_lshl_or_b32 v182, v142, 2, v143
	v_or_b32_e32 v176, s68, v182
	v_mov_b32_e32 v177, s69
	v_lshl_add_u64 v[180:181], v[176:177], 2, s[4:5]
	global_load_dwordx4 v[200:203], v[180:181], off offset:64
	v_lshl_or_b32 v184, v142, 2, v143
	v_add_u32_e32 v176, s81, v130
	v_mad_i64_i32 v[176:177], s[96:97], v176, s79, v[172:173]
	v_lshl_add_u64 v[182:183], v[176:177], 0, s[66:67]
	v_or_b32_e32 v185, 32, v184
	v_or_b32_e32 v178, s68, v185
	v_ashrrev_i32_e32 v179, 31, v178
	v_lshlrev_b64 v[178:179], 1, v[178:179]
	v_lshl_add_u64 v[180:181], v[182:183], 0, v[178:179]
	global_load_dwordx2 v[204:205], v[180:181], off
	v_lshl_or_b32 v180, v142, 2, v143
	v_or_b32_e32 v176, s68, v180
	v_mov_b32_e32 v177, s69
	v_lshl_add_u64 v[178:179], v[176:177], 2, s[4:5]
	global_load_dwordx4 v[206:209], v[178:179], off offset:128
	v_lshl_or_b32 v186, v142, 2, v143
	v_add_u32_e32 v176, s81, v130
	v_mad_i64_i32 v[176:177], s[96:97], v176, s79, v[172:173]
	v_lshl_add_u64 v[184:185], v[176:177], 0, s[66:67]
	v_or_b32_e32 v181, 48, v186
	v_or_b32_e32 v178, s68, v181
	v_ashrrev_i32_e32 v179, 31, v178
	v_lshlrev_b64 v[178:179], 1, v[178:179]
	v_lshl_add_u64 v[182:183], v[184:185], 0, v[178:179]
	global_load_dwordx2 v[210:211], v[182:183], off
	v_lshl_or_b32 v180, v142, 2, v143
	v_or_b32_e32 v176, s68, v180
	v_mov_b32_e32 v177, s69
	v_lshl_add_u64 v[178:179], v[176:177], 2, s[4:5]
	global_load_dwordx4 v[212:215], v[178:179], off offset:192
	v_lshl_or_b32 v186, v142, 2, v143
	v_or_b32_e32 v176, s68, v186
	v_ashrrev_i32_e32 v177, 31, v176
	v_lshlrev_b64 v[182:183], 1, v[176:177]
	v_or_b32_e32 v179, 16, v130
	v_add_u32_e32 v179, s81, v179
	v_mad_i64_i32 v[180:181], s[96:97], v179, s79, v[172:173]
	v_lshl_add_u64 v[180:181], v[180:181], 0, s[66:67]
	v_lshl_add_u64 v[184:185], v[180:181], 0, v[182:183]
	global_load_dwordx2 v[216:217], v[184:185], off
	v_lshl_or_b32 v188, v142, 2, v143
	v_or_b32_e32 v187, 16, v188
	v_or_b32_e32 v178, s68, v187
	v_ashrrev_i32_e32 v179, 31, v178
	v_lshlrev_b64 v[184:185], 1, v[178:179]
	v_or_b32_e32 v181, 16, v130
	v_add_u32_e32 v181, s81, v181
	v_mad_i64_i32 v[182:183], s[96:97], v181, s79, v[172:173]
	v_lshl_add_u64 v[182:183], v[182:183], 0, s[66:67]
	v_lshl_add_u64 v[176:177], v[182:183], 0, v[184:185]
	global_load_dwordx2 v[218:219], v[176:177], off
	v_lshl_or_b32 v184, v142, 2, v143
	v_or_b32_e32 v185, 32, v184
	v_or_b32_e32 v182, s68, v185
	v_ashrrev_i32_e32 v183, 31, v182
	v_lshlrev_b64 v[182:183], 1, v[182:183]
	v_or_b32_e32 v179, 16, v130
	v_add_u32_e32 v179, s81, v179
	v_mad_i64_i32 v[180:181], s[96:97], v179, s79, v[172:173]
	v_lshl_add_u64 v[180:181], v[180:181], 0, s[66:67]
	v_lshl_add_u64 v[176:177], v[180:181], 0, v[182:183]
	global_load_dwordx2 v[220:221], v[176:177], off
	v_lshl_or_b32 v186, v142, 2, v143
	v_or_b32_e32 v185, 48, v186
	v_or_b32_e32 v182, s68, v185
	v_ashrrev_i32_e32 v183, 31, v182
	v_lshlrev_b64 v[182:183], 1, v[182:183]
	v_or_b32_e32 v179, 16, v130
	v_add_u32_e32 v179, s81, v179
	v_mad_i64_i32 v[180:181], s[96:97], v179, s79, v[172:173]
	v_lshl_add_u64 v[180:181], v[180:181], 0, s[66:67]
	v_lshl_add_u64 v[176:177], v[180:181], 0, v[182:183]
	global_load_dwordx2 v[222:223], v[176:177], off
	v_lshl_or_b32 v184, v142, 2, v143
	v_or_b32_e32 v180, s68, v184
	v_ashrrev_i32_e32 v181, 31, v180
	v_lshlrev_b64 v[182:183], 1, v[180:181]
	v_or_b32_e32 v176, 32, v130
	v_add_u32_e32 v176, s81, v176
	v_mad_i64_i32 v[176:177], s[96:97], v176, s79, v[172:173]
	v_lshl_add_u64 v[178:179], v[176:177], 0, s[66:67]
	v_lshl_add_u64 v[176:177], v[178:179], 0, v[182:183]
	global_load_dwordx2 v[224:225], v[176:177], off
	v_lshl_or_b32 v188, v142, 2, v143
	v_or_b32_e32 v187, 16, v188
	v_or_b32_e32 v182, s68, v187
	v_ashrrev_i32_e32 v183, 31, v182
	v_lshlrev_b64 v[184:185], 1, v[182:183]
	v_or_b32_e32 v178, 32, v130
	v_add_u32_e32 v178, s81, v178
	v_mad_i64_i32 v[178:179], s[96:97], v178, s79, v[172:173]
	v_lshl_add_u64 v[180:181], v[178:179], 0, s[66:67]
	v_lshl_add_u64 v[176:177], v[180:181], 0, v[184:185]
	global_load_dwordx2 v[226:227], v[176:177], off
	v_lshl_or_b32 v184, v142, 2, v143
	v_or_b32_e32 v185, 32, v184
; template <int WT, class Epi>
; DEV void gemm_tile(const bf16_t* __restrict__ A, int lda, const bf16_t* __restrict__ Bt, int ldb, int K, unsigned char* lds, const Epi& epi) {
;     ...
;             for (int i = 0; i < FI; ++i) { af[i] = *(const bf16x8*)(lds + cur + aoff + i * 2048 + ch); bfr[i] = *(const bf16x8*)(lds + cur + boff + i * 2048 + ch); }
; #pragma unroll
;             for (int mi = 0; mi < FI; ++mi)
; #pragma unroll
;                 for (int ni = 0; ni < FI; ++ni) acc[mi][ni] = __builtin_amdgcn_mfma_f32_16x16x32_bf16(bfr[ni], af[mi], acc[mi][ni], 0, 0, 0);
;     DEV f32x4 xform(int r, int c, f32x4 v) const {
;         const int row = m0 + r, col = n0 + c;
;         const uint2 z = *(const uint2*)(proj + (size_t)row * NPJ + C_ZB + col);
;         const f32x4 s = *(const f32x4*)(scale + col);
	v_or_b32_e32 v182, s68, v185
	v_ashrrev_i32_e32 v183, 31, v182
	v_lshlrev_b64 v[182:183], 1, v[182:183]
	v_or_b32_e32 v178, 32, v130
	v_add_u32_e32 v178, s81, v178
	v_mad_i64_i32 v[178:179], s[96:97], v178, s79, v[172:173]
	v_lshl_add_u64 v[180:181], v[178:179], 0, s[66:67]
	v_lshl_add_u64 v[176:177], v[180:181], 0, v[182:183]
	global_load_dwordx2 v[228:229], v[176:177], off
	v_lshl_or_b32 v186, v142, 2, v143
	v_or_b32_e32 v185, 48, v186
	v_or_b32_e32 v182, s68, v185
	v_ashrrev_i32_e32 v183, 31, v182
	v_lshlrev_b64 v[182:183], 1, v[182:183]
	v_or_b32_e32 v178, 32, v130
	v_add_u32_e32 v178, s81, v178
	v_mad_i64_i32 v[178:179], s[96:97], v178, s79, v[172:173]
	v_lshl_add_u64 v[180:181], v[178:179], 0, s[66:67]
	v_lshl_add_u64 v[176:177], v[180:181], 0, v[182:183]
	global_load_dwordx2 v[230:231], v[176:177], off
	v_lshl_or_b32 v184, v142, 2, v143
	v_or_b32_e32 v180, s68, v184
	v_ashrrev_i32_e32 v181, 31, v180
	v_lshlrev_b64 v[182:183], 1, v[180:181]
	v_or_b32_e32 v176, 48, v130
	v_add_u32_e32 v176, s81, v176
	v_mad_i64_i32 v[176:177], s[96:97], v176, s79, v[172:173]
	v_lshl_add_u64 v[178:179], v[176:177], 0, s[66:67]
	v_lshl_add_u64 v[176:177], v[178:179], 0, v[182:183]
	global_load_dwordx2 v[232:233], v[176:177], off
	v_lshl_or_b32 v188, v142, 2, v143
	v_or_b32_e32 v187, 16, v188
	v_or_b32_e32 v182, s68, v187
	v_ashrrev_i32_e32 v183, 31, v182
	v_lshlrev_b64 v[184:185], 1, v[182:183]
	v_or_b32_e32 v178, 48, v130
	v_add_u32_e32 v178, s81, v178
	v_mad_i64_i32 v[178:179], s[96:97], v178, s79, v[172:173]
	v_lshl_add_u64 v[180:181], v[178:179], 0, s[66:67]
	v_lshl_add_u64 v[176:177], v[180:181], 0, v[184:185]
	global_load_dwordx2 v[234:235], v[176:177], off
	v_lshl_or_b32 v184, v142, 2, v143
	v_or_b32_e32 v185, 32, v184
	v_or_b32_e32 v182, s68, v185
	v_ashrrev_i32_e32 v183, 31, v182
	v_lshlrev_b64 v[182:183], 1, v[182:183]
	v_or_b32_e32 v178, 48, v130
	v_add_u32_e32 v178, s81, v178
	v_mad_i64_i32 v[178:179], s[96:97], v178, s79, v[172:173]
	v_lshl_add_u64 v[180:181], v[178:179], 0, s[66:67]
	v_lshl_add_u64 v[176:177], v[180:181], 0, v[182:183]
	global_load_dwordx2 v[236:237], v[176:177], off
	v_lshl_or_b32 v186, v142, 2, v143
	v_or_b32_e32 v185, 48, v186
	v_or_b32_e32 v182, s68, v185
	v_ashrrev_i32_e32 v183, 31, v182
	v_lshlrev_b64 v[182:183], 1, v[182:183]
	v_or_b32_e32 v178, 48, v130
	v_add_u32_e32 v178, s81, v178
	v_mad_i64_i32 v[178:179], s[96:97], v178, s79, v[172:173]
	v_lshl_add_u64 v[180:181], v[178:179], 0, s[66:67]
	v_lshl_add_u64 v[176:177], v[180:181], 0, v[182:183]
	global_load_dwordx2 v[238:239], v[176:177], off
	v_mfma_f32_16x16x32_bf16 v[18:21], v[118:121], v[126:129], v[18:21]
	v_mfma_f32_16x16x32_bf16 v[22:25], v[110:113], v[126:129], v[22:25]
	v_mfma_f32_16x16x32_bf16 v[26:29], v[106:109], v[126:129], v[26:29]
	v_mfma_f32_16x16x32_bf16 v[30:33], v[98:101], v[126:129], v[30:33]
	v_mfma_f32_16x16x32_bf16 v[34:37], v[118:121], v[122:125], v[34:37]
	v_mfma_f32_16x16x32_bf16 v[38:41], v[110:113], v[122:125], v[38:41]
	v_mfma_f32_16x16x32_bf16 v[126:129], v[106:109], v[122:125], v[50:53]
	v_mfma_f32_16x16x32_bf16 v[122:125], v[98:101], v[122:125], v[54:57]
	v_mfma_f32_16x16x32_bf16 v[144:147], v[118:121], v[114:117], v[58:61]
	v_mfma_f32_16x16x32_bf16 v[148:151], v[110:113], v[114:117], v[62:65]
	v_mfma_f32_16x16x32_bf16 v[66:69], v[106:109], v[114:117], v[66:69]
	v_mfma_f32_16x16x32_bf16 v[70:73], v[98:101], v[114:117], v[70:73]
	v_mfma_f32_16x16x32_bf16 v[74:77], v[118:121], v[102:105], v[74:77]
	v_mfma_f32_16x16x32_bf16 v[78:81], v[110:113], v[102:105], v[78:81]
	v_mfma_f32_16x16x32_bf16 v[82:85], v[106:109], v[102:105], v[82:85]
	v_mfma_f32_16x16x32_bf16 v[86:89], v[98:101], v[102:105], v[86:89]
	v_mfma_f32_16x16x32_bf16 v[98:101], v[46:49], v[94:97], v[18:21]
	v_mfma_f32_16x16x32_bf16 v[102:105], v[10:13], v[94:97], v[22:25]
	v_mfma_f32_16x16x32_bf16 v[62:65], v[6:9], v[94:97], v[26:29]
	v_mfma_f32_16x16x32_bf16 v[58:61], v[2:5], v[94:97], v[30:33]
	v_mfma_f32_16x16x32_bf16 v[54:57], v[46:49], v[90:93], v[34:37]
	v_mfma_f32_16x16x32_bf16 v[50:53], v[10:13], v[90:93], v[38:41]
	v_mfma_f32_16x16x32_bf16 v[38:41], v[6:9], v[90:93], v[126:129]
	v_mfma_f32_16x16x32_bf16 v[34:37], v[2:5], v[90:93], v[122:125]
	v_lshl_add_u32 v90, v130, 8, s70
	v_mfma_f32_16x16x32_bf16 v[30:33], v[46:49], v[14:17], v[144:147]
	v_mfma_f32_16x16x32_bf16 v[26:29], v[10:13], v[14:17], v[148:151]
	v_mfma_f32_16x16x32_bf16 v[22:25], v[6:9], v[14:17], v[66:69]
	v_mfma_f32_16x16x32_bf16 v[18:21], v[2:5], v[14:17], v[70:73]
	v_mfma_f32_16x16x32_bf16 v[14:17], v[46:49], v[42:45], v[74:77]
	v_mfma_f32_16x16x32_bf16 v[10:13], v[10:13], v[42:45], v[78:81]
	v_mfma_f32_16x16x32_bf16 v[6:9], v[6:9], v[42:45], v[82:85]
	v_mfma_f32_16x16x32_bf16 v[2:5], v[2:5], v[42:45], v[86:89]
	v_lshrrev_b32_e32 v42, 1, v137
	s_nop 1
	v_lshl_or_b32 v88, v142, 2, v143
	v_and_b32_e32 v89, 8, v42
	v_add_u32_e32 v42, s81, v130
	v_or_b32_e32 v46, s68, v88
	v_mad_i64_i32 v[42:43], s[82:83], v42, s79, v[172:173]
	v_ashrrev_i32_e32 v47, 31, v46
	v_lshl_add_u64 v[82:83], v[42:43], 0, s[66:67]
	v_lshlrev_b64 v[68:69], 1, v[46:47]
	v_lshl_add_u64 v[42:43], v[82:83], 0, v[68:69]

;     DEV f32x4 xform(int r, int c, f32x4 v) const {
;     ...
;         const f32x4 s = *(const f32x4*)(scale + col);
	v_lshl_add_u64 v[70:71], v[46:47], 2, s[4:5]

; DEV float bflo(unsigned u) { return __uint_as_float(u << 16); }
; DEV float bfhi(unsigned u) { return __uint_as_float(u & 0xffff0000u); }
; DEV float silu_f(float x) { return x / (1.f + __expf(-x)); }
;     DEV f32x4 xform(int r, int c, f32x4 v) const {
;         const int row = m0 + r, col = n0 + c;
;         const uint2 z = *(const uint2*)(proj + (size_t)row * NPJ + C_ZB + col);
;         const f32x4 s = *(const f32x4*)(scale + col);
;         f32x4 o;
;         o[0] = v[0] * s[0] * silu_f(bflo(z.x)); o[1] = v[1] * s[1] * silu_f(bfhi(z.x));
;         o[2] = v[2] * s[2] * silu_f(bflo(z.y)); o[3] = v[3] * s[3] * silu_f(bfhi(z.y));
	s_waitcnt vmcnt(1)
	v_lshlrev_b32_e32 v47, 16, v192
	v_and_b32_e32 v48, 0xffff0000, v192
	v_mul_f32_e32 v66, 0xbfb8aa3b, v47
	v_mul_f32_e32 v67, 0xbfb8aa3b, v48
	v_exp_f32_e32 v66, v66
	v_exp_f32_e32 v67, v67
	s_waitcnt vmcnt(0)
	v_pk_mul_f32 v[74:75], v[98:99], v[194:195]
	v_pk_mul_f32 v[72:73], v[100:101], v[196:197]
	v_pk_mul_f32 v[42:43], v[54:55], v[194:195]
	v_pk_add_f32 v[66:67], v[66:67], 1.0 op_sel_hi:[1,0]
	v_pk_mul_f32 v[44:45], v[56:57], v[196:197]


; DEV float silu_f(float x) { return x / (1.f + __expf(-x)); }
	s_nop 0


; DEV float silu_f(float x) { return x / (1.f + __expf(-x)); }
	v_rcp_f32_e32 v76, v67
	s_nop 0
	v_mul_f32_e32 v67, v48, v76


; DEV float silu_f(float x) { return x / (1.f + __expf(-x)); }
	s_nop 0


; DEV float bflo(unsigned u) { return __uint_as_float(u << 16); }
; DEV float bfhi(unsigned u) { return __uint_as_float(u & 0xffff0000u); }
; DEV float silu_f(float x) { return x / (1.f + __expf(-x)); }
;     DEV f32x4 xform(int r, int c, f32x4 v) const {
;     ...
;         o[0] = v[0] * s[0] * silu_f(bflo(z.x)); o[1] = v[1] * s[1] * silu_f(bfhi(z.x));
;         o[2] = v[2] * s[2] * silu_f(bflo(z.y)); o[3] = v[3] * s[3] * silu_f(bfhi(z.y));
	v_rcp_f32_e32 v48, v66
	s_nop 0
	v_mul_f32_e32 v66, v47, v48
	v_pk_mul_f32 v[66:67], v[74:75], v[66:67]
	v_lshlrev_b32_e32 v47, 16, v193
	v_and_b32_e32 v74, 0xffff0000, v193
	v_mul_f32_e32 v48, 0xbfb8aa3b, v47
	v_mul_f32_e32 v49, 0xbfb8aa3b, v74
	v_exp_f32_e32 v48, v48
	v_exp_f32_e32 v49, v49
	v_cvt_pk_bf16_f32 v66, v66, v67
	v_pk_add_f32 v[48:49], v[48:49], 1.0 op_sel_hi:[1,0]
	s_nop 0


; DEV float silu_f(float x) { return x / (1.f + __expf(-x)); }
	s_nop 0


; DEV float silu_f(float x) { return x / (1.f + __expf(-x)); }
	v_rcp_f32_e32 v75, v49
	s_nop 0
	v_mul_f32_e32 v49, v74, v75


; DEV float silu_f(float x) { return x / (1.f + __expf(-x)); }
	s_nop 0


; DEV float bflo(unsigned u) { return __uint_as_float(u << 16); }
; DEV float bfhi(unsigned u) { return __uint_as_float(u & 0xffff0000u); }
; DEV float silu_f(float x) { return x / (1.f + __expf(-x)); }
;     DEV f32x4 xform(int r, int c, f32x4 v) const {
;         const int row = m0 + r, col = n0 + c;
;         const uint2 z = *(const uint2*)(proj + (size_t)row * NPJ + C_ZB + col);
;         const f32x4 s = *(const f32x4*)(scale + col);
;         f32x4 o;
;         o[0] = v[0] * s[0] * silu_f(bflo(z.x)); o[1] = v[1] * s[1] * silu_f(bfhi(z.x));
;         o[2] = v[2] * s[2] * silu_f(bflo(z.y)); o[3] = v[3] * s[3] * silu_f(bfhi(z.y));
	v_rcp_f32_e32 v74, v48
	s_nop 0
	v_mul_f32_e32 v48, v47, v74
	v_pk_mul_f32 v[48:49], v[72:73], v[48:49]
	v_or_b32_e32 v77, 16, v88
	v_cvt_pk_bf16_f32 v67, v48, v49
	v_or_b32_e32 v48, s68, v77
	v_ashrrev_i32_e32 v49, 31, v48
	v_lshlrev_b64 v[72:73], 1, v[48:49]
	v_lshl_add_u64 v[48:49], v[82:83], 0, v[72:73]

; DEV unsigned cvt_pk_bf16(float lo, float hi) { const f32x2_t v = {lo, hi}; const bf16x2_t b = __builtin_convertvector(v, bf16x2_t); return __builtin_bit_cast(unsigned, b); }
; template <int WT, class Epi>
; DEV void gemm_tile(const bf16_t* __restrict__ A, int lda, const bf16_t* __restrict__ Bt, int ldb, int K, unsigned char* lds, const Epi& epi) {
;     ...
;                 const int row = wr * WT + mi * 16 + fr, col = wc * WT + ni * 16 + fq * 4;
;                 const f32x4 v = epi.xform(row, col, acc[mi][ni]);
;                 uint2 w; w.x = cvt_pk_bf16(v[0], v[1]); w.y = cvt_pk_bf16(v[2], v[3]);
;                 *(uint2*)(lds + row * RB + ((((col >> 3) ^ (row & (CPR - 1))) << 4) | (((col >> 2) & 1) << 3))) = w;
;     DEV f32x4 xform(int r, int c, f32x4 v) const {
;     ...
;         const f32x4 s = *(const f32x4*)(scale + col);
	v_lshrrev_b32_e32 v47, 3, v88
	v_bitop3_b32 v47, v47, v137, 15 bitop3:0x78
	v_lshl_or_b32 v76, v47, 4, v89
	v_add_u32_e32 v47, v90, v76
	ds_write_b64 v47, v[66:67]
	v_mov_b32_e32 v47, s69
	v_lshl_add_u64 v[66:67], v[46:47], 2, s[4:5]

; DEV float bflo(unsigned u) { return __uint_as_float(u << 16); }
; DEV float bfhi(unsigned u) { return __uint_as_float(u & 0xffff0000u); }
; DEV float silu_f(float x) { return x / (1.f + __expf(-x)); }
;     DEV f32x4 xform(int r, int c, f32x4 v) const {
;     ...
;         const uint2 z = *(const uint2*)(proj + (size_t)row * NPJ + C_ZB + col);
;         const f32x4 s = *(const f32x4*)(scale + col);
;         f32x4 o;
;         o[0] = v[0] * s[0] * silu_f(bflo(z.x)); o[1] = v[1] * s[1] * silu_f(bfhi(z.x));
;         o[2] = v[2] * s[2] * silu_f(bflo(z.y)); o[3] = v[3] * s[3] * silu_f(bfhi(z.y));
	s_waitcnt vmcnt(1)
	v_lshlrev_b32_e32 v86, 16, v198
	v_and_b32_e32 v74, 0xffff0000, v198
	v_mul_f32_e32 v78, 0xbfb8aa3b, v86
	v_mul_f32_e32 v79, 0xbfb8aa3b, v74
	v_exp_f32_e32 v78, v78
	v_exp_f32_e32 v79, v79
	s_waitcnt vmcnt(0)
	v_pk_mul_f32 v[84:85], v[102:103], v[200:201]
	v_pk_add_f32 v[78:79], v[78:79], 1.0 op_sel_hi:[1,0]
	v_pk_mul_f32 v[80:81], v[104:105], v[202:203]


; DEV float bflo(unsigned u) { return __uint_as_float(u << 16); }
; DEV float bfhi(unsigned u) { return __uint_as_float(u & 0xffff0000u); }
; DEV float silu_f(float x) { return x / (1.f + __expf(-x)); }
;     DEV f32x4 xform(int r, int c, f32x4 v) const {
;     ...
;         o[0] = v[0] * s[0] * silu_f(bflo(z.x)); o[1] = v[1] * s[1] * silu_f(bfhi(z.x));
;         o[2] = v[2] * s[2] * silu_f(bflo(z.y)); o[3] = v[3] * s[3] * silu_f(bfhi(z.y));
	v_pk_mul_f32 v[46:47], v[50:51], v[200:201]
	v_pk_mul_f32 v[48:49], v[52:53], v[202:203]


; DEV float silu_f(float x) { return x / (1.f + __expf(-x)); }
	v_rcp_f32_e32 v87, v79
	s_nop 0
	v_mul_f32_e32 v79, v74, v87


; DEV float silu_f(float x) { return x / (1.f + __expf(-x)); }
	s_nop 0


; DEV float bflo(unsigned u) { return __uint_as_float(u << 16); }
; DEV float bfhi(unsigned u) { return __uint_as_float(u & 0xffff0000u); }
; DEV float silu_f(float x) { return x / (1.f + __expf(-x)); }
;     DEV f32x4 xform(int r, int c, f32x4 v) const {
;     ...
;         o[0] = v[0] * s[0] * silu_f(bflo(z.x)); o[1] = v[1] * s[1] * silu_f(bfhi(z.x));
;         o[2] = v[2] * s[2] * silu_f(bflo(z.y)); o[3] = v[3] * s[3] * silu_f(bfhi(z.y));
	v_rcp_f32_e32 v74, v78
	s_nop 0
	v_mul_f32_e32 v78, v86, v74
	v_pk_mul_f32 v[78:79], v[84:85], v[78:79]
	v_lshlrev_b32_e32 v84, 16, v199
	v_and_b32_e32 v85, 0xffff0000, v199
	v_mul_f32_e32 v74, 0xbfb8aa3b, v84
	v_mul_f32_e32 v75, 0xbfb8aa3b, v85
	v_exp_f32_e32 v74, v74
	v_exp_f32_e32 v75, v75
	v_cvt_pk_bf16_f32 v78, v78, v79
	v_pk_add_f32 v[74:75], v[74:75], 1.0 op_sel_hi:[1,0]
	s_nop 0


; DEV float silu_f(float x) { return x / (1.f + __expf(-x)); }
	s_nop 0


; DEV float silu_f(float x) { return x / (1.f + __expf(-x)); }
	v_rcp_f32_e32 v86, v75
	s_nop 0
	v_mul_f32_e32 v75, v85, v86


; DEV float silu_f(float x) { return x / (1.f + __expf(-x)); }
	s_nop 0


; DEV unsigned cvt_pk_bf16(float lo, float hi) { const f32x2_t v = {lo, hi}; const bf16x2_t b = __builtin_convertvector(v, bf16x2_t); return __builtin_bit_cast(unsigned, b); }
; template <int WT, class Epi>
; DEV void gemm_tile(const bf16_t* __restrict__ A, int lda, const bf16_t* __restrict__ Bt, int ldb, int K, unsigned char* lds, const Epi& epi) {
;     ...
;                 const int row = wr * WT + mi * 16 + fr, col = wc * WT + ni * 16 + fq * 4;
;                 const f32x4 v = epi.xform(row, col, acc[mi][ni]);
;                 uint2 w; w.x = cvt_pk_bf16(v[0], v[1]); w.y = cvt_pk_bf16(v[2], v[3]);
;                 *(uint2*)(lds + row * RB + ((((col >> 3) ^ (row & (CPR - 1))) << 4) | (((col >> 2) & 1) << 3))) = w;
;     DEV f32x4 xform(int r, int c, f32x4 v) const {
;     ...
;         const uint2 z = *(const uint2*)(proj + (size_t)row * NPJ + C_ZB + col);
	v_rcp_f32_e32 v85, v74
	s_nop 0
	v_mul_f32_e32 v74, v84, v85
	v_pk_mul_f32 v[74:75], v[80:81], v[74:75]
	v_or_b32_e32 v91, 32, v88
	v_cvt_pk_bf16_f32 v79, v74, v75
	v_lshrrev_b32_e32 v74, 3, v77
	v_bitop3_b32 v74, v74, v137, 15 bitop3:0x78
	v_lshl_or_b32 v77, v74, 4, v89
	v_add_u32_e32 v74, v90, v77
	ds_write_b64 v74, v[78:79]
	v_or_b32_e32 v74, s68, v91
	v_ashrrev_i32_e32 v75, 31, v74
	v_lshlrev_b64 v[74:75], 1, v[74:75]
	v_lshl_add_u64 v[78:79], v[82:83], 0, v[74:75]

;     DEV f32x4 xform(int r, int c, f32x4 v) const {
;     ...
;         const f32x4 s = *(const f32x4*)(scale + col);
	s_nop 0

; DEV float bflo(unsigned u) { return __uint_as_float(u << 16); }
; DEV float bfhi(unsigned u) { return __uint_as_float(u & 0xffff0000u); }
; DEV float silu_f(float x) { return x / (1.f + __expf(-x)); }
;     DEV f32x4 xform(int r, int c, f32x4 v) const {
;     ...
;         const uint2 z = *(const uint2*)(proj + (size_t)row * NPJ + C_ZB + col);
;         const f32x4 s = *(const f32x4*)(scale + col);
;         f32x4 o;
;         o[0] = v[0] * s[0] * silu_f(bflo(z.x)); o[1] = v[1] * s[1] * silu_f(bfhi(z.x));
;         o[2] = v[2] * s[2] * silu_f(bflo(z.y)); o[3] = v[3] * s[3] * silu_f(bfhi(z.y));
	s_waitcnt vmcnt(1)
	v_lshlrev_b32_e32 v92, 16, v204
	v_and_b32_e32 v84, 0xffff0000, v204
	v_mul_f32_e32 v86, 0xbfb8aa3b, v92
	s_waitcnt vmcnt(0)
	v_pk_mul_f32 v[62:63], v[62:63], v[206:207]
	v_mul_f32_e32 v78, 0xbfb8aa3b, v84
	v_exp_f32_e32 v86, v86
	v_exp_f32_e32 v87, v78
	v_pk_mul_f32 v[64:65], v[64:65], v[208:209]
	v_pk_add_f32 v[78:79], v[86:87], 1.0 op_sel_hi:[1,0]
	s_nop 0


; DEV float silu_f(float x) { return x / (1.f + __expf(-x)); }
	s_nop 0


; DEV float silu_f(float x) { return x / (1.f + __expf(-x)); }
	v_rcp_f32_e32 v80, v79
	s_nop 0
	v_mul_f32_e32 v79, v84, v80


; DEV float silu_f(float x) { return x / (1.f + __expf(-x)); }
	s_nop 0


; DEV float bflo(unsigned u) { return __uint_as_float(u << 16); }
; DEV float bfhi(unsigned u) { return __uint_as_float(u & 0xffff0000u); }
; DEV float silu_f(float x) { return x / (1.f + __expf(-x)); }
;     DEV f32x4 xform(int r, int c, f32x4 v) const {
;     ...
;         o[0] = v[0] * s[0] * silu_f(bflo(z.x)); o[1] = v[1] * s[1] * silu_f(bfhi(z.x));
;         o[2] = v[2] * s[2] * silu_f(bflo(z.y)); o[3] = v[3] * s[3] * silu_f(bfhi(z.y));
	v_rcp_f32_e32 v80, v78
	s_nop 0
	v_mul_f32_e32 v78, v92, v80
	v_lshlrev_b32_e32 v80, 16, v205
	v_and_b32_e32 v81, 0xffff0000, v205
	v_pk_mul_f32 v[62:63], v[62:63], v[78:79]
	v_mul_f32_e32 v78, 0xbfb8aa3b, v80
	v_mul_f32_e32 v79, 0xbfb8aa3b, v81
	v_exp_f32_e32 v78, v78
	v_exp_f32_e32 v79, v79
	v_cvt_pk_bf16_f32 v62, v62, v63
	v_pk_add_f32 v[78:79], v[78:79], 1.0 op_sel_hi:[1,0]
	s_nop 0


; DEV float silu_f(float x) { return x / (1.f + __expf(-x)); }
	s_nop 0


; DEV float silu_f(float x) { return x / (1.f + __expf(-x)); }
	v_rcp_f32_e32 v84, v79
	s_nop 0
	v_mul_f32_e32 v79, v81, v84


; DEV float silu_f(float x) { return x / (1.f + __expf(-x)); }
	s_nop 0


; DEV unsigned cvt_pk_bf16(float lo, float hi) { const f32x2_t v = {lo, hi}; const bf16x2_t b = __builtin_convertvector(v, bf16x2_t); return __builtin_bit_cast(unsigned, b); }
; template <int WT, class Epi>
; DEV void gemm_tile(const bf16_t* __restrict__ A, int lda, const bf16_t* __restrict__ Bt, int ldb, int K, unsigned char* lds, const Epi& epi) {
;     ...
;                 const int row = wr * WT + mi * 16 + fr, col = wc * WT + ni * 16 + fq * 4;
;                 const f32x4 v = epi.xform(row, col, acc[mi][ni]);
;                 uint2 w; w.x = cvt_pk_bf16(v[0], v[1]); w.y = cvt_pk_bf16(v[2], v[3]);
;                 *(uint2*)(lds + row * RB + ((((col >> 3) ^ (row & (CPR - 1))) << 4) | (((col >> 2) & 1) << 3))) = w;
;     DEV f32x4 xform(int r, int c, f32x4 v) const {
;     ...
;         const uint2 z = *(const uint2*)(proj + (size_t)row * NPJ + C_ZB + col);
	v_rcp_f32_e32 v81, v78
	s_nop 0
	v_mul_f32_e32 v78, v80, v81
	v_pk_mul_f32 v[64:65], v[64:65], v[78:79]
	s_nop 0
	v_cvt_pk_bf16_f32 v63, v64, v65
	v_lshrrev_b32_e32 v64, 3, v91
	v_bitop3_b32 v64, v64, v137, 15 bitop3:0x78
	v_lshl_or_b32 v64, v64, 4, v89
	v_add_u32_e32 v65, v90, v64
	ds_write_b64 v65, v[62:63]
	v_or_b32_e32 v65, 48, v88
	v_or_b32_e32 v62, s68, v65
	v_ashrrev_i32_e32 v63, 31, v62
	v_lshlrev_b64 v[62:63], 1, v[62:63]
	v_lshl_add_u64 v[78:79], v[82:83], 0, v[62:63]

;     DEV f32x4 xform(int r, int c, f32x4 v) const {
;     ...
;         const f32x4 s = *(const f32x4*)(scale + col);
	s_nop 0

; DEV float bflo(unsigned u) { return __uint_as_float(u << 16); }
; DEV float bfhi(unsigned u) { return __uint_as_float(u & 0xffff0000u); }
; DEV float silu_f(float x) { return x / (1.f + __expf(-x)); }
;     DEV f32x4 xform(int r, int c, f32x4 v) const {
;     ...
;         const uint2 z = *(const uint2*)(proj + (size_t)row * NPJ + C_ZB + col);
;         const f32x4 s = *(const f32x4*)(scale + col);
;         f32x4 o;
;         o[0] = v[0] * s[0] * silu_f(bflo(z.x)); o[1] = v[1] * s[1] * silu_f(bfhi(z.x));
;         o[2] = v[2] * s[2] * silu_f(bflo(z.y)); o[3] = v[3] * s[3] * silu_f(bfhi(z.y));
	s_waitcnt vmcnt(1)
	v_lshlrev_b32_e32 v86, 16, v210
	v_and_b32_e32 v82, 0xffff0000, v210
	v_mul_f32_e32 v84, 0xbfb8aa3b, v86
	s_waitcnt vmcnt(0)
	v_pk_mul_f32 v[58:59], v[58:59], v[212:213]
	v_mul_f32_e32 v78, 0xbfb8aa3b, v82
	v_exp_f32_e32 v84, v84
	v_exp_f32_e32 v85, v78
	v_pk_mul_f32 v[60:61], v[60:61], v[214:215]
	v_pk_add_f32 v[78:79], v[84:85], 1.0 op_sel_hi:[1,0]
	s_nop 0


; DEV float silu_f(float x) { return x / (1.f + __expf(-x)); }
	s_nop 0


; DEV float silu_f(float x) { return x / (1.f + __expf(-x)); }
	v_rcp_f32_e32 v80, v79
	s_nop 0
	v_mul_f32_e32 v79, v82, v80


; DEV float silu_f(float x) { return x / (1.f + __expf(-x)); }
	s_nop 0


; DEV float bflo(unsigned u) { return __uint_as_float(u << 16); }
; DEV float bfhi(unsigned u) { return __uint_as_float(u & 0xffff0000u); }
; DEV float silu_f(float x) { return x / (1.f + __expf(-x)); }
;     DEV f32x4 xform(int r, int c, f32x4 v) const {
;     ...
;         o[0] = v[0] * s[0] * silu_f(bflo(z.x)); o[1] = v[1] * s[1] * silu_f(bfhi(z.x));
;         o[2] = v[2] * s[2] * silu_f(bflo(z.y)); o[3] = v[3] * s[3] * silu_f(bfhi(z.y));
	v_rcp_f32_e32 v80, v78
	s_nop 0
	v_mul_f32_e32 v78, v86, v80
	v_lshlrev_b32_e32 v80, 16, v211
	v_and_b32_e32 v81, 0xffff0000, v211
	v_pk_mul_f32 v[58:59], v[58:59], v[78:79]
	v_mul_f32_e32 v78, 0xbfb8aa3b, v80
	v_mul_f32_e32 v79, 0xbfb8aa3b, v81
	v_exp_f32_e32 v78, v78
	v_exp_f32_e32 v79, v79
	s_nop 0
	v_pk_add_f32 v[78:79], v[78:79], 1.0 op_sel_hi:[1,0]
	s_nop 0


; DEV float silu_f(float x) { return x / (1.f + __expf(-x)); }
	s_nop 0


; DEV float silu_f(float x) { return x / (1.f + __expf(-x)); }
	v_rcp_f32_e32 v82, v79
	s_nop 0
	v_mul_f32_e32 v79, v81, v82


; DEV float silu_f(float x) { return x / (1.f + __expf(-x)); }
	s_nop 0


; DEV unsigned cvt_pk_bf16(float lo, float hi) { const f32x2_t v = {lo, hi}; const bf16x2_t b = __builtin_convertvector(v, bf16x2_t); return __builtin_bit_cast(unsigned, b); }
; template <int WT, class Epi>
; DEV void gemm_tile(const bf16_t* __restrict__ A, int lda, const bf16_t* __restrict__ Bt, int ldb, int K, unsigned char* lds, const Epi& epi) {
;     ...
;                 const int row = wr * WT + mi * 16 + fr, col = wc * WT + ni * 16 + fq * 4;
;                 const f32x4 v = epi.xform(row, col, acc[mi][ni]);
;                 uint2 w; w.x = cvt_pk_bf16(v[0], v[1]); w.y = cvt_pk_bf16(v[2], v[3]);
;                 *(uint2*)(lds + row * RB + ((((col >> 3) ^ (row & (CPR - 1))) << 4) | (((col >> 2) & 1) << 3))) = w;
;     DEV f32x4 xform(int r, int c, f32x4 v) const {
;         const int row = m0 + r, col = n0 + c;
;         const uint2 z = *(const uint2*)(proj + (size_t)row * NPJ + C_ZB + col);
	v_rcp_f32_e32 v81, v78
	s_nop 0
	v_mul_f32_e32 v78, v80, v81
	v_pk_mul_f32 v[60:61], v[60:61], v[78:79]
	v_cvt_pk_bf16_f32 v78, v58, v59
	v_lshrrev_b32_e32 v58, 3, v65
	v_bitop3_b32 v58, v58, v137, 15 bitop3:0x78
	v_lshl_or_b32 v58, v58, 4, v89
	v_cvt_pk_bf16_f32 v79, v60, v61
	v_add_u32_e32 v59, v90, v58
	ds_write_b64 v59, v[78:79]
	v_or_b32_e32 v59, 16, v130
	v_lshl_add_u32 v65, v59, 8, s70
	v_add_u32_e32 v59, s81, v59
	v_mad_i64_i32 v[60:61], s[68:69], v59, s79, v[172:173]
	v_lshl_add_u64 v[60:61], v[60:61], 0, s[66:67]
	v_lshl_add_u64 v[78:79], v[60:61], 0, v[68:69]

; DEV float bflo(unsigned u) { return __uint_as_float(u << 16); }
; DEV float bfhi(unsigned u) { return __uint_as_float(u & 0xffff0000u); }
; DEV float silu_f(float x) { return x / (1.f + __expf(-x)); }
;     DEV f32x4 xform(int r, int c, f32x4 v) const {
;     ...
;         const uint2 z = *(const uint2*)(proj + (size_t)row * NPJ + C_ZB + col);
;         const f32x4 s = *(const f32x4*)(scale + col);
;         f32x4 o;
;         o[0] = v[0] * s[0] * silu_f(bflo(z.x)); o[1] = v[1] * s[1] * silu_f(bfhi(z.x));
;         o[2] = v[2] * s[2] * silu_f(bflo(z.y)); o[3] = v[3] * s[3] * silu_f(bfhi(z.y));
	s_waitcnt vmcnt(0)
	v_lshlrev_b32_e32 v59, 16, v216
	v_and_b32_e32 v78, 0xffff0000, v216
	v_mul_f32_e32 v80, 0xbfb8aa3b, v59
	v_mul_f32_e32 v54, 0xbfb8aa3b, v78
	v_exp_f32_e32 v80, v80
	v_exp_f32_e32 v81, v54
	s_nop 0
	v_pk_add_f32 v[54:55], v[80:81], 1.0 op_sel_hi:[1,0]
	s_nop 0


; DEV float silu_f(float x) { return x / (1.f + __expf(-x)); }
	s_nop 0


; DEV float silu_f(float x) { return x / (1.f + __expf(-x)); }
	v_rcp_f32_e32 v56, v55
	s_nop 0
	v_mul_f32_e32 v55, v78, v56


; DEV float silu_f(float x) { return x / (1.f + __expf(-x)); }
	s_nop 0


; DEV float bflo(unsigned u) { return __uint_as_float(u << 16); }
; DEV float bfhi(unsigned u) { return __uint_as_float(u & 0xffff0000u); }
; DEV float silu_f(float x) { return x / (1.f + __expf(-x)); }
;     DEV f32x4 xform(int r, int c, f32x4 v) const {
;     ...
;         o[0] = v[0] * s[0] * silu_f(bflo(z.x)); o[1] = v[1] * s[1] * silu_f(bfhi(z.x));
;         o[2] = v[2] * s[2] * silu_f(bflo(z.y)); o[3] = v[3] * s[3] * silu_f(bfhi(z.y));
	v_rcp_f32_e32 v56, v54
	s_nop 0
	v_mul_f32_e32 v54, v59, v56
	v_lshlrev_b32_e32 v56, 16, v217
	v_and_b32_e32 v57, 0xffff0000, v217
	v_pk_mul_f32 v[42:43], v[42:43], v[54:55]
	v_mul_f32_e32 v54, 0xbfb8aa3b, v56
	v_mul_f32_e32 v55, 0xbfb8aa3b, v57
	v_exp_f32_e32 v54, v54
	v_exp_f32_e32 v55, v55
	v_cvt_pk_bf16_f32 v42, v42, v43
	v_pk_add_f32 v[54:55], v[54:55], 1.0 op_sel_hi:[1,0]
	s_nop 0


; DEV float silu_f(float x) { return x / (1.f + __expf(-x)); }
	s_nop 0


; DEV float silu_f(float x) { return x / (1.f + __expf(-x)); }
	v_rcp_f32_e32 v59, v55
	s_nop 0
	v_mul_f32_e32 v55, v57, v59


; DEV float silu_f(float x) { return x / (1.f + __expf(-x)); }
	s_nop 0


; DEV unsigned cvt_pk_bf16(float lo, float hi) { const f32x2_t v = {lo, hi}; const bf16x2_t b = __builtin_convertvector(v, bf16x2_t); return __builtin_bit_cast(unsigned, b); }
; template <int WT, class Epi>
; DEV void gemm_tile(const bf16_t* __restrict__ A, int lda, const bf16_t* __restrict__ Bt, int ldb, int K, unsigned char* lds, const Epi& epi) {
;     ...
;                 const int row = wr * WT + mi * 16 + fr, col = wc * WT + ni * 16 + fq * 4;
;                 const f32x4 v = epi.xform(row, col, acc[mi][ni]);
;                 uint2 w; w.x = cvt_pk_bf16(v[0], v[1]); w.y = cvt_pk_bf16(v[2], v[3]);
;                 *(uint2*)(lds + row * RB + ((((col >> 3) ^ (row & (CPR - 1))) << 4) | (((col >> 2) & 1) << 3))) = w;
;     DEV f32x4 xform(int r, int c, f32x4 v) const {
;     ...
;         const uint2 z = *(const uint2*)(proj + (size_t)row * NPJ + C_ZB + col);
	v_rcp_f32_e32 v57, v54
	s_nop 0
	v_mul_f32_e32 v54, v56, v57
	v_pk_mul_f32 v[44:45], v[44:45], v[54:55]
	s_nop 0
	v_cvt_pk_bf16_f32 v43, v44, v45
	v_add_u32_e32 v44, v65, v76
	ds_write_b64 v44, v[42:43]
	v_lshl_add_u64 v[42:43], v[60:61], 0, v[72:73]

; DEV float bflo(unsigned u) { return __uint_as_float(u << 16); }
; DEV float bfhi(unsigned u) { return __uint_as_float(u & 0xffff0000u); }
; DEV float silu_f(float x) { return x / (1.f + __expf(-x)); }
;     DEV f32x4 xform(int r, int c, f32x4 v) const {
;     ...
;         const uint2 z = *(const uint2*)(proj + (size_t)row * NPJ + C_ZB + col);
;         const f32x4 s = *(const f32x4*)(scale + col);
;         f32x4 o;
;         o[0] = v[0] * s[0] * silu_f(bflo(z.x)); o[1] = v[1] * s[1] * silu_f(bfhi(z.x));
;         o[2] = v[2] * s[2] * silu_f(bflo(z.y)); o[3] = v[3] * s[3] * silu_f(bfhi(z.y));
	s_waitcnt vmcnt(0)
	v_lshlrev_b32_e32 v54, 16, v218
	v_and_b32_e32 v42, 0xffff0000, v218
	v_mul_f32_e32 v44, 0xbfb8aa3b, v54
	v_mul_f32_e32 v45, 0xbfb8aa3b, v42
	v_exp_f32_e32 v44, v44
	v_exp_f32_e32 v45, v45
	s_nop 0
	v_pk_add_f32 v[44:45], v[44:45], 1.0 op_sel_hi:[1,0]
	s_nop 0


; DEV float bflo(unsigned u) { return __uint_as_float(u << 16); }
; DEV float bfhi(unsigned u) { return __uint_as_float(u & 0xffff0000u); }
; DEV float silu_f(float x) { return x / (1.f + __expf(-x)); }
;     DEV f32x4 xform(int r, int c, f32x4 v) const {
;     ...
;         o[0] = v[0] * s[0] * silu_f(bflo(z.x)); o[1] = v[1] * s[1] * silu_f(bfhi(z.x));
;         o[2] = v[2] * s[2] * silu_f(bflo(z.y)); o[3] = v[3] * s[3] * silu_f(bfhi(z.y));
	s_nop 0


; DEV float silu_f(float x) { return x / (1.f + __expf(-x)); }
	v_rcp_f32_e32 v50, v45
	s_nop 0
	v_mul_f32_e32 v45, v42, v50


; DEV float bflo(unsigned u) { return __uint_as_float(u << 16); }
; DEV float bfhi(unsigned u) { return __uint_as_float(u & 0xffff0000u); }
; DEV float silu_f(float x) { return x / (1.f + __expf(-x)); }
;     DEV f32x4 xform(int r, int c, f32x4 v) const {
;     ...
;         o[0] = v[0] * s[0] * silu_f(bflo(z.x)); o[1] = v[1] * s[1] * silu_f(bfhi(z.x));
;         o[2] = v[2] * s[2] * silu_f(bflo(z.y)); o[3] = v[3] * s[3] * silu_f(bfhi(z.y));
	s_nop 0


; DEV unsigned cvt_pk_bf16(float lo, float hi) { const f32x2_t v = {lo, hi}; const bf16x2_t b = __builtin_convertvector(v, bf16x2_t); return __builtin_bit_cast(unsigned, b); }
; DEV float bflo(unsigned u) { return __uint_as_float(u << 16); }
; DEV float bfhi(unsigned u) { return __uint_as_float(u & 0xffff0000u); }
; DEV float silu_f(float x) { return x / (1.f + __expf(-x)); }
; template <int WT, class Epi>
; DEV void gemm_tile(const bf16_t* __restrict__ A, int lda, const bf16_t* __restrict__ Bt, int ldb, int K, unsigned char* lds, const Epi& epi) {
;     ...
;                 uint2 w; w.x = cvt_pk_bf16(v[0], v[1]); w.y = cvt_pk_bf16(v[2], v[3]);
;     DEV f32x4 xform(int r, int c, f32x4 v) const {
;     ...
;         o[0] = v[0] * s[0] * silu_f(bflo(z.x)); o[1] = v[1] * s[1] * silu_f(bfhi(z.x));
;         o[2] = v[2] * s[2] * silu_f(bflo(z.y)); o[3] = v[3] * s[3] * silu_f(bfhi(z.y));
	v_rcp_f32_e32 v42, v44
	s_nop 0
	v_mul_f32_e32 v44, v54, v42
	v_pk_mul_f32 v[44:45], v[46:47], v[44:45]
	v_lshlrev_b32_e32 v46, 16, v219
	v_and_b32_e32 v47, 0xffff0000, v219
	v_mul_f32_e32 v42, 0xbfb8aa3b, v46
	v_mul_f32_e32 v43, 0xbfb8aa3b, v47
	v_exp_f32_e32 v42, v42
	v_exp_f32_e32 v43, v43
	v_cvt_pk_bf16_f32 v44, v44, v45
	v_pk_add_f32 v[42:43], v[42:43], 1.0 op_sel_hi:[1,0]
	s_nop 0


; DEV float bflo(unsigned u) { return __uint_as_float(u << 16); }
; DEV float bfhi(unsigned u) { return __uint_as_float(u & 0xffff0000u); }
; DEV float silu_f(float x) { return x / (1.f + __expf(-x)); }
;     DEV f32x4 xform(int r, int c, f32x4 v) const {
;     ...
;         o[0] = v[0] * s[0] * silu_f(bflo(z.x)); o[1] = v[1] * s[1] * silu_f(bfhi(z.x));
;         o[2] = v[2] * s[2] * silu_f(bflo(z.y)); o[3] = v[3] * s[3] * silu_f(bfhi(z.y));
	s_nop 0


; DEV float silu_f(float x) { return x / (1.f + __expf(-x)); }
	v_rcp_f32_e32 v50, v43
	s_nop 0
	v_mul_f32_e32 v43, v47, v50


; DEV float bflo(unsigned u) { return __uint_as_float(u << 16); }
; DEV float bfhi(unsigned u) { return __uint_as_float(u & 0xffff0000u); }
; DEV float silu_f(float x) { return x / (1.f + __expf(-x)); }
;     DEV f32x4 xform(int r, int c, f32x4 v) const {
;     ...
;         o[0] = v[0] * s[0] * silu_f(bflo(z.x)); o[1] = v[1] * s[1] * silu_f(bfhi(z.x));
;         o[2] = v[2] * s[2] * silu_f(bflo(z.y)); o[3] = v[3] * s[3] * silu_f(bfhi(z.y));
	s_nop 0


; DEV unsigned cvt_pk_bf16(float lo, float hi) { const f32x2_t v = {lo, hi}; const bf16x2_t b = __builtin_convertvector(v, bf16x2_t); return __builtin_bit_cast(unsigned, b); }
; DEV float bflo(unsigned u) { return __uint_as_float(u << 16); }
; DEV float bfhi(unsigned u) { return __uint_as_float(u & 0xffff0000u); }
; DEV float silu_f(float x) { return x / (1.f + __expf(-x)); }
; template <int WT, class Epi>
; DEV void gemm_tile(const bf16_t* __restrict__ A, int lda, const bf16_t* __restrict__ Bt, int ldb, int K, unsigned char* lds, const Epi& epi) {
;     ...
;                 const int row = wr * WT + mi * 16 + fr, col = wc * WT + ni * 16 + fq * 4;
;                 const f32x4 v = epi.xform(row, col, acc[mi][ni]);
;                 uint2 w; w.x = cvt_pk_bf16(v[0], v[1]); w.y = cvt_pk_bf16(v[2], v[3]);
;                 *(uint2*)(lds + row * RB + ((((col >> 3) ^ (row & (CPR - 1))) << 4) | (((col >> 2) & 1) << 3))) = w;
;     DEV f32x4 xform(int r, int c, f32x4 v) const {
;     ...
;         o[0] = v[0] * s[0] * silu_f(bflo(z.x)); o[1] = v[1] * s[1] * silu_f(bfhi(z.x));
;         o[2] = v[2] * s[2] * silu_f(bflo(z.y)); o[3] = v[3] * s[3] * silu_f(bfhi(z.y));
	v_rcp_f32_e32 v47, v42
	s_nop 0
	v_mul_f32_e32 v42, v46, v47
	v_pk_mul_f32 v[42:43], v[48:49], v[42:43]
	s_nop 0
	v_cvt_pk_bf16_f32 v45, v42, v43
	v_add_u32_e32 v42, v65, v77
	ds_write_b64 v42, v[44:45]
	v_lshl_add_u64 v[42:43], v[60:61], 0, v[74:75]

;     DEV f32x4 xform(int r, int c, f32x4 v) const {
;     ...
;         const f32x4 s = *(const f32x4*)(scale + col);
	s_nop 0

; DEV float bflo(unsigned u) { return __uint_as_float(u << 16); }
; DEV float bfhi(unsigned u) { return __uint_as_float(u & 0xffff0000u); }
; DEV float silu_f(float x) { return x / (1.f + __expf(-x)); }
;     DEV f32x4 xform(int r, int c, f32x4 v) const {
;     ...
;         const uint2 z = *(const uint2*)(proj + (size_t)row * NPJ + C_ZB + col);
;         const f32x4 s = *(const f32x4*)(scale + col);
;         f32x4 o;
;         o[0] = v[0] * s[0] * silu_f(bflo(z.x)); o[1] = v[1] * s[1] * silu_f(bfhi(z.x));
;         o[2] = v[2] * s[2] * silu_f(bflo(z.y)); o[3] = v[3] * s[3] * silu_f(bfhi(z.y));
	s_waitcnt vmcnt(1)
	v_lshlrev_b32_e32 v50, 16, v220
	v_and_b32_e32 v46, 0xffff0000, v220
	v_mul_f32_e32 v48, 0xbfb8aa3b, v50
	s_waitcnt vmcnt(0)
	v_pk_mul_f32 v[38:39], v[38:39], v[206:207]
	v_mul_f32_e32 v42, 0xbfb8aa3b, v46
	v_exp_f32_e32 v48, v48
	v_exp_f32_e32 v49, v42
	v_pk_mul_f32 v[40:41], v[40:41], v[208:209]
	v_pk_add_f32 v[42:43], v[48:49], 1.0 op_sel_hi:[1,0]
	s_nop 0


; DEV float bflo(unsigned u) { return __uint_as_float(u << 16); }
; DEV float bfhi(unsigned u) { return __uint_as_float(u & 0xffff0000u); }
; DEV float silu_f(float x) { return x / (1.f + __expf(-x)); }
;     DEV f32x4 xform(int r, int c, f32x4 v) const {
;     ...
;         o[0] = v[0] * s[0] * silu_f(bflo(z.x)); o[1] = v[1] * s[1] * silu_f(bfhi(z.x));
;         o[2] = v[2] * s[2] * silu_f(bflo(z.y)); o[3] = v[3] * s[3] * silu_f(bfhi(z.y));
	s_nop 0


; DEV float silu_f(float x) { return x / (1.f + __expf(-x)); }
	v_rcp_f32_e32 v44, v43
	s_nop 0
	v_mul_f32_e32 v43, v46, v44


; DEV float bflo(unsigned u) { return __uint_as_float(u << 16); }
; DEV float bfhi(unsigned u) { return __uint_as_float(u & 0xffff0000u); }
; DEV float silu_f(float x) { return x / (1.f + __expf(-x)); }
;     DEV f32x4 xform(int r, int c, f32x4 v) const {
;     ...
;         o[0] = v[0] * s[0] * silu_f(bflo(z.x)); o[1] = v[1] * s[1] * silu_f(bfhi(z.x));
;         o[2] = v[2] * s[2] * silu_f(bflo(z.y)); o[3] = v[3] * s[3] * silu_f(bfhi(z.y));
	s_nop 0


; DEV float bflo(unsigned u) { return __uint_as_float(u << 16); }
; DEV float bfhi(unsigned u) { return __uint_as_float(u & 0xffff0000u); }
; DEV float silu_f(float x) { return x / (1.f + __expf(-x)); }
;     DEV f32x4 xform(int r, int c, f32x4 v) const {
;     ...
;         o[0] = v[0] * s[0] * silu_f(bflo(z.x)); o[1] = v[1] * s[1] * silu_f(bfhi(z.x));
;         o[2] = v[2] * s[2] * silu_f(bflo(z.y)); o[3] = v[3] * s[3] * silu_f(bfhi(z.y));
	v_rcp_f32_e32 v44, v42
	s_nop 0
	v_mul_f32_e32 v42, v50, v44
	v_lshlrev_b32_e32 v44, 16, v221
	v_and_b32_e32 v45, 0xffff0000, v221
	v_pk_mul_f32 v[38:39], v[38:39], v[42:43]
	v_mul_f32_e32 v42, 0xbfb8aa3b, v44
	v_mul_f32_e32 v43, 0xbfb8aa3b, v45
	v_exp_f32_e32 v42, v42
	v_exp_f32_e32 v43, v43
	v_cvt_pk_bf16_f32 v38, v38, v39
	v_pk_add_f32 v[42:43], v[42:43], 1.0 op_sel_hi:[1,0]
	s_nop 0


; DEV float bflo(unsigned u) { return __uint_as_float(u << 16); }
; DEV float bfhi(unsigned u) { return __uint_as_float(u & 0xffff0000u); }
; DEV float silu_f(float x) { return x / (1.f + __expf(-x)); }
;     DEV f32x4 xform(int r, int c, f32x4 v) const {
;     ...
;         o[0] = v[0] * s[0] * silu_f(bflo(z.x)); o[1] = v[1] * s[1] * silu_f(bfhi(z.x));
;         o[2] = v[2] * s[2] * silu_f(bflo(z.y)); o[3] = v[3] * s[3] * silu_f(bfhi(z.y));
	s_nop 0


; DEV float silu_f(float x) { return x / (1.f + __expf(-x)); }
	v_rcp_f32_e32 v46, v43
	s_nop 0
	v_mul_f32_e32 v43, v45, v46


; DEV float bflo(unsigned u) { return __uint_as_float(u << 16); }
; DEV float bfhi(unsigned u) { return __uint_as_float(u & 0xffff0000u); }
; DEV float silu_f(float x) { return x / (1.f + __expf(-x)); }
;     DEV f32x4 xform(int r, int c, f32x4 v) const {
;     ...
;         o[0] = v[0] * s[0] * silu_f(bflo(z.x)); o[1] = v[1] * s[1] * silu_f(bfhi(z.x));
;         o[2] = v[2] * s[2] * silu_f(bflo(z.y)); o[3] = v[3] * s[3] * silu_f(bfhi(z.y));
	s_nop 0


; DEV unsigned cvt_pk_bf16(float lo, float hi) { const f32x2_t v = {lo, hi}; const bf16x2_t b = __builtin_convertvector(v, bf16x2_t); return __builtin_bit_cast(unsigned, b); }
; DEV float bflo(unsigned u) { return __uint_as_float(u << 16); }
; DEV float bfhi(unsigned u) { return __uint_as_float(u & 0xffff0000u); }
; DEV float silu_f(float x) { return x / (1.f + __expf(-x)); }
; template <int WT, class Epi>
; DEV void gemm_tile(const bf16_t* __restrict__ A, int lda, const bf16_t* __restrict__ Bt, int ldb, int K, unsigned char* lds, const Epi& epi) {
;     ...
;                 const int row = wr * WT + mi * 16 + fr, col = wc * WT + ni * 16 + fq * 4;
;                 const f32x4 v = epi.xform(row, col, acc[mi][ni]);
;                 uint2 w; w.x = cvt_pk_bf16(v[0], v[1]); w.y = cvt_pk_bf16(v[2], v[3]);
;                 *(uint2*)(lds + row * RB + ((((col >> 3) ^ (row & (CPR - 1))) << 4) | (((col >> 2) & 1) << 3))) = w;
;     DEV f32x4 xform(int r, int c, f32x4 v) const {
;     ...
;         o[0] = v[0] * s[0] * silu_f(bflo(z.x)); o[1] = v[1] * s[1] * silu_f(bfhi(z.x));
;         o[2] = v[2] * s[2] * silu_f(bflo(z.y)); o[3] = v[3] * s[3] * silu_f(bfhi(z.y));
	v_rcp_f32_e32 v45, v42
	s_nop 0
	v_mul_f32_e32 v42, v44, v45
	v_pk_mul_f32 v[40:41], v[40:41], v[42:43]
	s_nop 0
	v_cvt_pk_bf16_f32 v39, v40, v41
	v_add_u32_e32 v40, v65, v64
	ds_write_b64 v40, v[38:39]
	v_lshl_add_u64 v[38:39], v[60:61], 0, v[62:63]

;     DEV f32x4 xform(int r, int c, f32x4 v) const {
;     ...
;         const f32x4 s = *(const f32x4*)(scale + col);
	s_nop 0

; DEV float bflo(unsigned u) { return __uint_as_float(u << 16); }
; DEV float bfhi(unsigned u) { return __uint_as_float(u & 0xffff0000u); }
; DEV float silu_f(float x) { return x / (1.f + __expf(-x)); }
;     DEV f32x4 xform(int r, int c, f32x4 v) const {
;     ...
;         const uint2 z = *(const uint2*)(proj + (size_t)row * NPJ + C_ZB + col);
;         const f32x4 s = *(const f32x4*)(scale + col);
;         f32x4 o;
;         o[0] = v[0] * s[0] * silu_f(bflo(z.x)); o[1] = v[1] * s[1] * silu_f(bfhi(z.x));
;         o[2] = v[2] * s[2] * silu_f(bflo(z.y)); o[3] = v[3] * s[3] * silu_f(bfhi(z.y));
	s_waitcnt vmcnt(1)
	v_lshlrev_b32_e32 v46, 16, v222
	v_and_b32_e32 v42, 0xffff0000, v222
	v_mul_f32_e32 v44, 0xbfb8aa3b, v46
	s_waitcnt vmcnt(0)
	v_pk_mul_f32 v[34:35], v[34:35], v[212:213]
	v_mul_f32_e32 v38, 0xbfb8aa3b, v42
	v_exp_f32_e32 v44, v44
	v_exp_f32_e32 v45, v38
	v_pk_mul_f32 v[36:37], v[36:37], v[214:215]
	v_pk_add_f32 v[38:39], v[44:45], 1.0 op_sel_hi:[1,0]
	s_nop 0


; DEV float bflo(unsigned u) { return __uint_as_float(u << 16); }
; DEV float bfhi(unsigned u) { return __uint_as_float(u & 0xffff0000u); }
; DEV float silu_f(float x) { return x / (1.f + __expf(-x)); }
;     DEV f32x4 xform(int r, int c, f32x4 v) const {
;     ...
;         o[0] = v[0] * s[0] * silu_f(bflo(z.x)); o[1] = v[1] * s[1] * silu_f(bfhi(z.x));
;         o[2] = v[2] * s[2] * silu_f(bflo(z.y)); o[3] = v[3] * s[3] * silu_f(bfhi(z.y));
	s_nop 0


; DEV float silu_f(float x) { return x / (1.f + __expf(-x)); }
	v_rcp_f32_e32 v40, v39
	s_nop 0
	v_mul_f32_e32 v39, v42, v40


; DEV float bflo(unsigned u) { return __uint_as_float(u << 16); }
; DEV float bfhi(unsigned u) { return __uint_as_float(u & 0xffff0000u); }
; DEV float silu_f(float x) { return x / (1.f + __expf(-x)); }
;     DEV f32x4 xform(int r, int c, f32x4 v) const {
;     ...
;         o[0] = v[0] * s[0] * silu_f(bflo(z.x)); o[1] = v[1] * s[1] * silu_f(bfhi(z.x));
;         o[2] = v[2] * s[2] * silu_f(bflo(z.y)); o[3] = v[3] * s[3] * silu_f(bfhi(z.y));
	s_nop 0


; DEV float bflo(unsigned u) { return __uint_as_float(u << 16); }
; DEV float bfhi(unsigned u) { return __uint_as_float(u & 0xffff0000u); }
; DEV float silu_f(float x) { return x / (1.f + __expf(-x)); }
;     DEV f32x4 xform(int r, int c, f32x4 v) const {
;     ...
;         o[0] = v[0] * s[0] * silu_f(bflo(z.x)); o[1] = v[1] * s[1] * silu_f(bfhi(z.x));
;         o[2] = v[2] * s[2] * silu_f(bflo(z.y)); o[3] = v[3] * s[3] * silu_f(bfhi(z.y));
	v_rcp_f32_e32 v40, v38
	s_nop 0
	v_mul_f32_e32 v38, v46, v40
	v_lshlrev_b32_e32 v40, 16, v223
	v_and_b32_e32 v41, 0xffff0000, v223
	v_pk_mul_f32 v[34:35], v[34:35], v[38:39]
	v_mul_f32_e32 v38, 0xbfb8aa3b, v40
	v_mul_f32_e32 v39, 0xbfb8aa3b, v41
	v_exp_f32_e32 v38, v38
	v_exp_f32_e32 v39, v39
	v_cvt_pk_bf16_f32 v34, v34, v35
	v_pk_add_f32 v[38:39], v[38:39], 1.0 op_sel_hi:[1,0]
	s_nop 0


; DEV float bflo(unsigned u) { return __uint_as_float(u << 16); }
; DEV float bfhi(unsigned u) { return __uint_as_float(u & 0xffff0000u); }
; DEV float silu_f(float x) { return x / (1.f + __expf(-x)); }
;     DEV f32x4 xform(int r, int c, f32x4 v) const {
;     ...
;         o[0] = v[0] * s[0] * silu_f(bflo(z.x)); o[1] = v[1] * s[1] * silu_f(bfhi(z.x));
;         o[2] = v[2] * s[2] * silu_f(bflo(z.y)); o[3] = v[3] * s[3] * silu_f(bfhi(z.y));
	s_nop 0


; DEV float silu_f(float x) { return x / (1.f + __expf(-x)); }
	v_rcp_f32_e32 v42, v39
	s_nop 0
	v_mul_f32_e32 v39, v41, v42


; DEV float bflo(unsigned u) { return __uint_as_float(u << 16); }
; DEV float bfhi(unsigned u) { return __uint_as_float(u & 0xffff0000u); }
; DEV float silu_f(float x) { return x / (1.f + __expf(-x)); }
;     DEV f32x4 xform(int r, int c, f32x4 v) const {
;     ...
;         o[0] = v[0] * s[0] * silu_f(bflo(z.x)); o[1] = v[1] * s[1] * silu_f(bfhi(z.x));
;         o[2] = v[2] * s[2] * silu_f(bflo(z.y)); o[3] = v[3] * s[3] * silu_f(bfhi(z.y));
	s_nop 0


; DEV unsigned cvt_pk_bf16(float lo, float hi) { const f32x2_t v = {lo, hi}; const bf16x2_t b = __builtin_convertvector(v, bf16x2_t); return __builtin_bit_cast(unsigned, b); }
; template <int WT, class Epi>
; DEV void gemm_tile(const bf16_t* __restrict__ A, int lda, const bf16_t* __restrict__ Bt, int ldb, int K, unsigned char* lds, const Epi& epi) {
;     ...
;                 const int row = wr * WT + mi * 16 + fr, col = wc * WT + ni * 16 + fq * 4;
;                 const f32x4 v = epi.xform(row, col, acc[mi][ni]);
;                 uint2 w; w.x = cvt_pk_bf16(v[0], v[1]); w.y = cvt_pk_bf16(v[2], v[3]);
;                 *(uint2*)(lds + row * RB + ((((col >> 3) ^ (row & (CPR - 1))) << 4) | (((col >> 2) & 1) << 3))) = w;
;     DEV f32x4 xform(int r, int c, f32x4 v) const {
;     ...
;         const uint2 z = *(const uint2*)(proj + (size_t)row * NPJ + C_ZB + col);
	v_rcp_f32_e32 v41, v38
	s_nop 0
	v_mul_f32_e32 v38, v40, v41
	v_pk_mul_f32 v[36:37], v[36:37], v[38:39]
	s_nop 0
	v_cvt_pk_bf16_f32 v35, v36, v37
	v_add_u32_e32 v36, v65, v58
	ds_write_b64 v36, v[34:35]
	v_or_b32_e32 v34, 32, v130
	v_lshl_add_u32 v44, v34, 8, s70
	v_add_u32_e32 v34, s81, v34
	v_mad_i64_i32 v[34:35], s[68:69], v34, s79, v[172:173]
	v_lshl_add_u64 v[38:39], v[34:35], 0, s[66:67]
	v_lshl_add_u64 v[34:35], v[38:39], 0, v[68:69]

;     DEV f32x4 xform(int r, int c, f32x4 v) const {
;     ...
;         const f32x4 s = *(const f32x4*)(scale + col);
	s_nop 0

; DEV float bflo(unsigned u) { return __uint_as_float(u << 16); }
; DEV float bfhi(unsigned u) { return __uint_as_float(u & 0xffff0000u); }
; DEV float silu_f(float x) { return x / (1.f + __expf(-x)); }
;     DEV f32x4 xform(int r, int c, f32x4 v) const {
;     ...
;         const uint2 z = *(const uint2*)(proj + (size_t)row * NPJ + C_ZB + col);
;         const f32x4 s = *(const f32x4*)(scale + col);
;         f32x4 o;
;         o[0] = v[0] * s[0] * silu_f(bflo(z.x)); o[1] = v[1] * s[1] * silu_f(bfhi(z.x));
;         o[2] = v[2] * s[2] * silu_f(bflo(z.y)); o[3] = v[3] * s[3] * silu_f(bfhi(z.y));
	s_waitcnt vmcnt(1)
	v_lshlrev_b32_e32 v45, 16, v224
	v_and_b32_e32 v40, 0xffff0000, v224
	v_mul_f32_e32 v42, 0xbfb8aa3b, v45
	s_waitcnt vmcnt(0)
	v_pk_mul_f32 v[30:31], v[30:31], v[194:195]
	v_mul_f32_e32 v34, 0xbfb8aa3b, v40
	v_exp_f32_e32 v42, v42
	v_exp_f32_e32 v43, v34
	v_pk_mul_f32 v[32:33], v[32:33], v[196:197]
	v_pk_add_f32 v[34:35], v[42:43], 1.0 op_sel_hi:[1,0]
	s_nop 0


; DEV float bflo(unsigned u) { return __uint_as_float(u << 16); }
; DEV float bfhi(unsigned u) { return __uint_as_float(u & 0xffff0000u); }
; DEV float silu_f(float x) { return x / (1.f + __expf(-x)); }
;     DEV f32x4 xform(int r, int c, f32x4 v) const {
;     ...
;         o[0] = v[0] * s[0] * silu_f(bflo(z.x)); o[1] = v[1] * s[1] * silu_f(bfhi(z.x));
;         o[2] = v[2] * s[2] * silu_f(bflo(z.y)); o[3] = v[3] * s[3] * silu_f(bfhi(z.y));
	s_nop 0


; DEV float silu_f(float x) { return x / (1.f + __expf(-x)); }
	v_rcp_f32_e32 v36, v35
	s_nop 0
	v_mul_f32_e32 v35, v40, v36


; DEV float bflo(unsigned u) { return __uint_as_float(u << 16); }
; DEV float bfhi(unsigned u) { return __uint_as_float(u & 0xffff0000u); }
; DEV float silu_f(float x) { return x / (1.f + __expf(-x)); }
;     DEV f32x4 xform(int r, int c, f32x4 v) const {
;     ...
;         o[0] = v[0] * s[0] * silu_f(bflo(z.x)); o[1] = v[1] * s[1] * silu_f(bfhi(z.x));
;         o[2] = v[2] * s[2] * silu_f(bflo(z.y)); o[3] = v[3] * s[3] * silu_f(bfhi(z.y));
	s_nop 0


; DEV float bflo(unsigned u) { return __uint_as_float(u << 16); }
; DEV float bfhi(unsigned u) { return __uint_as_float(u & 0xffff0000u); }
; DEV float silu_f(float x) { return x / (1.f + __expf(-x)); }
;     DEV f32x4 xform(int r, int c, f32x4 v) const {
;     ...
;         o[0] = v[0] * s[0] * silu_f(bflo(z.x)); o[1] = v[1] * s[1] * silu_f(bfhi(z.x));
;         o[2] = v[2] * s[2] * silu_f(bflo(z.y)); o[3] = v[3] * s[3] * silu_f(bfhi(z.y));
	v_rcp_f32_e32 v36, v34
	s_nop 0
	v_mul_f32_e32 v34, v45, v36
	v_lshlrev_b32_e32 v36, 16, v225
	v_and_b32_e32 v37, 0xffff0000, v225
	v_pk_mul_f32 v[30:31], v[30:31], v[34:35]
	v_mul_f32_e32 v34, 0xbfb8aa3b, v36
	v_mul_f32_e32 v35, 0xbfb8aa3b, v37
	v_exp_f32_e32 v34, v34
	v_exp_f32_e32 v35, v35
	v_cvt_pk_bf16_f32 v30, v30, v31
	v_pk_add_f32 v[34:35], v[34:35], 1.0 op_sel_hi:[1,0]
	s_nop 0


; DEV float bflo(unsigned u) { return __uint_as_float(u << 16); }
; DEV float bfhi(unsigned u) { return __uint_as_float(u & 0xffff0000u); }
; DEV float silu_f(float x) { return x / (1.f + __expf(-x)); }
;     DEV f32x4 xform(int r, int c, f32x4 v) const {
;     ...
;         o[0] = v[0] * s[0] * silu_f(bflo(z.x)); o[1] = v[1] * s[1] * silu_f(bfhi(z.x));
;         o[2] = v[2] * s[2] * silu_f(bflo(z.y)); o[3] = v[3] * s[3] * silu_f(bfhi(z.y));
	s_nop 0


; DEV float silu_f(float x) { return x / (1.f + __expf(-x)); }
	v_rcp_f32_e32 v40, v35
	s_nop 0
	v_mul_f32_e32 v35, v37, v40


; DEV float bflo(unsigned u) { return __uint_as_float(u << 16); }
; DEV float bfhi(unsigned u) { return __uint_as_float(u & 0xffff0000u); }
; DEV float silu_f(float x) { return x / (1.f + __expf(-x)); }
;     DEV f32x4 xform(int r, int c, f32x4 v) const {
;     ...
;         o[0] = v[0] * s[0] * silu_f(bflo(z.x)); o[1] = v[1] * s[1] * silu_f(bfhi(z.x));
;         o[2] = v[2] * s[2] * silu_f(bflo(z.y)); o[3] = v[3] * s[3] * silu_f(bfhi(z.y));
	s_nop 0


; DEV unsigned cvt_pk_bf16(float lo, float hi) { const f32x2_t v = {lo, hi}; const bf16x2_t b = __builtin_convertvector(v, bf16x2_t); return __builtin_bit_cast(unsigned, b); }
; DEV float bflo(unsigned u) { return __uint_as_float(u << 16); }
; DEV float bfhi(unsigned u) { return __uint_as_float(u & 0xffff0000u); }
; DEV float silu_f(float x) { return x / (1.f + __expf(-x)); }
; template <int WT, class Epi>
; DEV void gemm_tile(const bf16_t* __restrict__ A, int lda, const bf16_t* __restrict__ Bt, int ldb, int K, unsigned char* lds, const Epi& epi) {
;     ...
;                 const int row = wr * WT + mi * 16 + fr, col = wc * WT + ni * 16 + fq * 4;
;                 const f32x4 v = epi.xform(row, col, acc[mi][ni]);
;                 uint2 w; w.x = cvt_pk_bf16(v[0], v[1]); w.y = cvt_pk_bf16(v[2], v[3]);
;                 *(uint2*)(lds + row * RB + ((((col >> 3) ^ (row & (CPR - 1))) << 4) | (((col >> 2) & 1) << 3))) = w;
;     DEV f32x4 xform(int r, int c, f32x4 v) const {
;     ...
;         o[0] = v[0] * s[0] * silu_f(bflo(z.x)); o[1] = v[1] * s[1] * silu_f(bfhi(z.x));
;         o[2] = v[2] * s[2] * silu_f(bflo(z.y)); o[3] = v[3] * s[3] * silu_f(bfhi(z.y));
	v_rcp_f32_e32 v37, v34
	s_nop 0
	v_mul_f32_e32 v34, v36, v37
	v_pk_mul_f32 v[32:33], v[32:33], v[34:35]
	s_nop 0
	v_cvt_pk_bf16_f32 v31, v32, v33
	v_add_u32_e32 v32, v44, v76
	ds_write_b64 v32, v[30:31]
	v_lshl_add_u64 v[30:31], v[38:39], 0, v[72:73]

;     DEV f32x4 xform(int r, int c, f32x4 v) const {
;     ...
;         const f32x4 s = *(const f32x4*)(scale + col);
	s_nop 0

; DEV float bflo(unsigned u) { return __uint_as_float(u << 16); }
; DEV float bfhi(unsigned u) { return __uint_as_float(u & 0xffff0000u); }
; DEV float silu_f(float x) { return x / (1.f + __expf(-x)); }
;     DEV f32x4 xform(int r, int c, f32x4 v) const {
;     ...
;         const uint2 z = *(const uint2*)(proj + (size_t)row * NPJ + C_ZB + col);
;         const f32x4 s = *(const f32x4*)(scale + col);
;         f32x4 o;
;         o[0] = v[0] * s[0] * silu_f(bflo(z.x)); o[1] = v[1] * s[1] * silu_f(bfhi(z.x));
;         o[2] = v[2] * s[2] * silu_f(bflo(z.y)); o[3] = v[3] * s[3] * silu_f(bfhi(z.y));
	s_waitcnt vmcnt(1)
	v_lshlrev_b32_e32 v40, 16, v226
	v_and_b32_e32 v34, 0xffff0000, v226
	v_mul_f32_e32 v36, 0xbfb8aa3b, v40
	s_waitcnt vmcnt(0)
	v_pk_mul_f32 v[26:27], v[26:27], v[200:201]
	v_mul_f32_e32 v30, 0xbfb8aa3b, v34
	v_exp_f32_e32 v36, v36
	v_exp_f32_e32 v37, v30
	v_pk_mul_f32 v[28:29], v[28:29], v[202:203]
	v_pk_add_f32 v[30:31], v[36:37], 1.0 op_sel_hi:[1,0]
	s_nop 0


; DEV float bflo(unsigned u) { return __uint_as_float(u << 16); }
; DEV float bfhi(unsigned u) { return __uint_as_float(u & 0xffff0000u); }
; DEV float silu_f(float x) { return x / (1.f + __expf(-x)); }
;     DEV f32x4 xform(int r, int c, f32x4 v) const {
;     ...
;         o[0] = v[0] * s[0] * silu_f(bflo(z.x)); o[1] = v[1] * s[1] * silu_f(bfhi(z.x));
;         o[2] = v[2] * s[2] * silu_f(bflo(z.y)); o[3] = v[3] * s[3] * silu_f(bfhi(z.y));
	s_nop 0


; DEV float silu_f(float x) { return x / (1.f + __expf(-x)); }
	v_rcp_f32_e32 v32, v31
	s_nop 0
	v_mul_f32_e32 v31, v34, v32


; DEV float bflo(unsigned u) { return __uint_as_float(u << 16); }
; DEV float bfhi(unsigned u) { return __uint_as_float(u & 0xffff0000u); }
; DEV float silu_f(float x) { return x / (1.f + __expf(-x)); }
;     DEV f32x4 xform(int r, int c, f32x4 v) const {
;     ...
;         o[0] = v[0] * s[0] * silu_f(bflo(z.x)); o[1] = v[1] * s[1] * silu_f(bfhi(z.x));
;         o[2] = v[2] * s[2] * silu_f(bflo(z.y)); o[3] = v[3] * s[3] * silu_f(bfhi(z.y));
	s_nop 0


; DEV float bflo(unsigned u) { return __uint_as_float(u << 16); }
; DEV float bfhi(unsigned u) { return __uint_as_float(u & 0xffff0000u); }
; DEV float silu_f(float x) { return x / (1.f + __expf(-x)); }
;     DEV f32x4 xform(int r, int c, f32x4 v) const {
;     ...
;         o[0] = v[0] * s[0] * silu_f(bflo(z.x)); o[1] = v[1] * s[1] * silu_f(bfhi(z.x));
;         o[2] = v[2] * s[2] * silu_f(bflo(z.y)); o[3] = v[3] * s[3] * silu_f(bfhi(z.y));
	v_rcp_f32_e32 v32, v30
	s_nop 0
	v_mul_f32_e32 v30, v40, v32
	v_lshlrev_b32_e32 v32, 16, v227
	v_and_b32_e32 v33, 0xffff0000, v227
	v_pk_mul_f32 v[26:27], v[26:27], v[30:31]
	v_mul_f32_e32 v30, 0xbfb8aa3b, v32
	v_mul_f32_e32 v31, 0xbfb8aa3b, v33
	v_exp_f32_e32 v30, v30
	v_exp_f32_e32 v31, v31
	v_cvt_pk_bf16_f32 v26, v26, v27
	v_pk_add_f32 v[30:31], v[30:31], 1.0 op_sel_hi:[1,0]
	s_nop 0


; DEV float bflo(unsigned u) { return __uint_as_float(u << 16); }
; DEV float bfhi(unsigned u) { return __uint_as_float(u & 0xffff0000u); }
; DEV float silu_f(float x) { return x / (1.f + __expf(-x)); }
;     DEV f32x4 xform(int r, int c, f32x4 v) const {
;     ...
;         o[0] = v[0] * s[0] * silu_f(bflo(z.x)); o[1] = v[1] * s[1] * silu_f(bfhi(z.x));
;         o[2] = v[2] * s[2] * silu_f(bflo(z.y)); o[3] = v[3] * s[3] * silu_f(bfhi(z.y));
	s_nop 0


; DEV float silu_f(float x) { return x / (1.f + __expf(-x)); }
	v_rcp_f32_e32 v34, v31
	s_nop 0
	v_mul_f32_e32 v31, v33, v34


; DEV float bflo(unsigned u) { return __uint_as_float(u << 16); }
; DEV float bfhi(unsigned u) { return __uint_as_float(u & 0xffff0000u); }
; DEV float silu_f(float x) { return x / (1.f + __expf(-x)); }
;     DEV f32x4 xform(int r, int c, f32x4 v) const {
;     ...
;         o[0] = v[0] * s[0] * silu_f(bflo(z.x)); o[1] = v[1] * s[1] * silu_f(bfhi(z.x));
;         o[2] = v[2] * s[2] * silu_f(bflo(z.y)); o[3] = v[3] * s[3] * silu_f(bfhi(z.y));
	s_nop 0


; DEV unsigned cvt_pk_bf16(float lo, float hi) { const f32x2_t v = {lo, hi}; const bf16x2_t b = __builtin_convertvector(v, bf16x2_t); return __builtin_bit_cast(unsigned, b); }
; DEV float bflo(unsigned u) { return __uint_as_float(u << 16); }
; DEV float bfhi(unsigned u) { return __uint_as_float(u & 0xffff0000u); }
; DEV float silu_f(float x) { return x / (1.f + __expf(-x)); }
; template <int WT, class Epi>
; DEV void gemm_tile(const bf16_t* __restrict__ A, int lda, const bf16_t* __restrict__ Bt, int ldb, int K, unsigned char* lds, const Epi& epi) {
;     ...
;                 const int row = wr * WT + mi * 16 + fr, col = wc * WT + ni * 16 + fq * 4;
;                 const f32x4 v = epi.xform(row, col, acc[mi][ni]);
;                 uint2 w; w.x = cvt_pk_bf16(v[0], v[1]); w.y = cvt_pk_bf16(v[2], v[3]);
;                 *(uint2*)(lds + row * RB + ((((col >> 3) ^ (row & (CPR - 1))) << 4) | (((col >> 2) & 1) << 3))) = w;
;     DEV f32x4 xform(int r, int c, f32x4 v) const {
;     ...
;         o[0] = v[0] * s[0] * silu_f(bflo(z.x)); o[1] = v[1] * s[1] * silu_f(bfhi(z.x));
;         o[2] = v[2] * s[2] * silu_f(bflo(z.y)); o[3] = v[3] * s[3] * silu_f(bfhi(z.y));
	v_rcp_f32_e32 v33, v30
	s_nop 0
	v_mul_f32_e32 v30, v32, v33
	v_pk_mul_f32 v[28:29], v[28:29], v[30:31]
	s_nop 0
	v_cvt_pk_bf16_f32 v27, v28, v29
	v_add_u32_e32 v28, v44, v77
	ds_write_b64 v28, v[26:27]
	v_lshl_add_u64 v[26:27], v[38:39], 0, v[74:75]

;     DEV f32x4 xform(int r, int c, f32x4 v) const {
;     ...
;         const f32x4 s = *(const f32x4*)(scale + col);
	s_nop 0

; DEV float bflo(unsigned u) { return __uint_as_float(u << 16); }
; DEV float bfhi(unsigned u) { return __uint_as_float(u & 0xffff0000u); }
; DEV float silu_f(float x) { return x / (1.f + __expf(-x)); }
;     DEV f32x4 xform(int r, int c, f32x4 v) const {
;     ...
;         const uint2 z = *(const uint2*)(proj + (size_t)row * NPJ + C_ZB + col);
;         const f32x4 s = *(const f32x4*)(scale + col);
;         f32x4 o;
;         o[0] = v[0] * s[0] * silu_f(bflo(z.x)); o[1] = v[1] * s[1] * silu_f(bfhi(z.x));
;         o[2] = v[2] * s[2] * silu_f(bflo(z.y)); o[3] = v[3] * s[3] * silu_f(bfhi(z.y));
	s_waitcnt vmcnt(1)
	v_lshlrev_b32_e32 v34, 16, v228
	v_and_b32_e32 v30, 0xffff0000, v228
	v_mul_f32_e32 v32, 0xbfb8aa3b, v34
	s_waitcnt vmcnt(0)
	v_pk_mul_f32 v[22:23], v[22:23], v[206:207]
	v_mul_f32_e32 v26, 0xbfb8aa3b, v30
	v_exp_f32_e32 v32, v32
	v_exp_f32_e32 v33, v26
	v_pk_mul_f32 v[24:25], v[24:25], v[208:209]
	v_pk_add_f32 v[26:27], v[32:33], 1.0 op_sel_hi:[1,0]
	s_nop 0


; DEV float bflo(unsigned u) { return __uint_as_float(u << 16); }
; DEV float bfhi(unsigned u) { return __uint_as_float(u & 0xffff0000u); }
; DEV float silu_f(float x) { return x / (1.f + __expf(-x)); }
;     DEV f32x4 xform(int r, int c, f32x4 v) const {
;     ...
;         o[0] = v[0] * s[0] * silu_f(bflo(z.x)); o[1] = v[1] * s[1] * silu_f(bfhi(z.x));
;         o[2] = v[2] * s[2] * silu_f(bflo(z.y)); o[3] = v[3] * s[3] * silu_f(bfhi(z.y));
	s_nop 0


; DEV float silu_f(float x) { return x / (1.f + __expf(-x)); }
	v_rcp_f32_e32 v28, v27
	s_nop 0
	v_mul_f32_e32 v27, v30, v28


; DEV float bflo(unsigned u) { return __uint_as_float(u << 16); }
; DEV float bfhi(unsigned u) { return __uint_as_float(u & 0xffff0000u); }
; DEV float silu_f(float x) { return x / (1.f + __expf(-x)); }
;     DEV f32x4 xform(int r, int c, f32x4 v) const {
;     ...
;         o[0] = v[0] * s[0] * silu_f(bflo(z.x)); o[1] = v[1] * s[1] * silu_f(bfhi(z.x));
;         o[2] = v[2] * s[2] * silu_f(bflo(z.y)); o[3] = v[3] * s[3] * silu_f(bfhi(z.y));
	s_nop 0


; DEV float bflo(unsigned u) { return __uint_as_float(u << 16); }
; DEV float bfhi(unsigned u) { return __uint_as_float(u & 0xffff0000u); }
; DEV float silu_f(float x) { return x / (1.f + __expf(-x)); }
;     DEV f32x4 xform(int r, int c, f32x4 v) const {
;     ...
;         o[0] = v[0] * s[0] * silu_f(bflo(z.x)); o[1] = v[1] * s[1] * silu_f(bfhi(z.x));
;         o[2] = v[2] * s[2] * silu_f(bflo(z.y)); o[3] = v[3] * s[3] * silu_f(bfhi(z.y));
	v_rcp_f32_e32 v28, v26
	s_nop 0
	v_mul_f32_e32 v26, v34, v28
	v_lshlrev_b32_e32 v28, 16, v229
	v_and_b32_e32 v29, 0xffff0000, v229
	v_pk_mul_f32 v[22:23], v[22:23], v[26:27]
	v_mul_f32_e32 v26, 0xbfb8aa3b, v28
	v_mul_f32_e32 v27, 0xbfb8aa3b, v29
	v_exp_f32_e32 v26, v26
	v_exp_f32_e32 v27, v27
	v_cvt_pk_bf16_f32 v22, v22, v23
	v_pk_add_f32 v[26:27], v[26:27], 1.0 op_sel_hi:[1,0]
	s_nop 0


; DEV float bflo(unsigned u) { return __uint_as_float(u << 16); }
; DEV float bfhi(unsigned u) { return __uint_as_float(u & 0xffff0000u); }
; DEV float silu_f(float x) { return x / (1.f + __expf(-x)); }
;     DEV f32x4 xform(int r, int c, f32x4 v) const {
;     ...
;         o[0] = v[0] * s[0] * silu_f(bflo(z.x)); o[1] = v[1] * s[1] * silu_f(bfhi(z.x));
;         o[2] = v[2] * s[2] * silu_f(bflo(z.y)); o[3] = v[3] * s[3] * silu_f(bfhi(z.y));
	s_nop 0


; DEV float silu_f(float x) { return x / (1.f + __expf(-x)); }
	v_rcp_f32_e32 v30, v27
	s_nop 0
	v_mul_f32_e32 v27, v29, v30


; DEV float bflo(unsigned u) { return __uint_as_float(u << 16); }
; DEV float bfhi(unsigned u) { return __uint_as_float(u & 0xffff0000u); }
; DEV float silu_f(float x) { return x / (1.f + __expf(-x)); }
;     DEV f32x4 xform(int r, int c, f32x4 v) const {
;     ...
;         o[0] = v[0] * s[0] * silu_f(bflo(z.x)); o[1] = v[1] * s[1] * silu_f(bfhi(z.x));
;         o[2] = v[2] * s[2] * silu_f(bflo(z.y)); o[3] = v[3] * s[3] * silu_f(bfhi(z.y));
	s_nop 0


; DEV unsigned cvt_pk_bf16(float lo, float hi) { const f32x2_t v = {lo, hi}; const bf16x2_t b = __builtin_convertvector(v, bf16x2_t); return __builtin_bit_cast(unsigned, b); }
; DEV float bflo(unsigned u) { return __uint_as_float(u << 16); }
; DEV float bfhi(unsigned u) { return __uint_as_float(u & 0xffff0000u); }
; DEV float silu_f(float x) { return x / (1.f + __expf(-x)); }
; template <int WT, class Epi>
; DEV void gemm_tile(const bf16_t* __restrict__ A, int lda, const bf16_t* __restrict__ Bt, int ldb, int K, unsigned char* lds, const Epi& epi) {
;     ...
;                 const int row = wr * WT + mi * 16 + fr, col = wc * WT + ni * 16 + fq * 4;
;                 const f32x4 v = epi.xform(row, col, acc[mi][ni]);
;                 uint2 w; w.x = cvt_pk_bf16(v[0], v[1]); w.y = cvt_pk_bf16(v[2], v[3]);
;                 *(uint2*)(lds + row * RB + ((((col >> 3) ^ (row & (CPR - 1))) << 4) | (((col >> 2) & 1) << 3))) = w;
;     DEV f32x4 xform(int r, int c, f32x4 v) const {
;     ...
;         o[0] = v[0] * s[0] * silu_f(bflo(z.x)); o[1] = v[1] * s[1] * silu_f(bfhi(z.x));
;         o[2] = v[2] * s[2] * silu_f(bflo(z.y)); o[3] = v[3] * s[3] * silu_f(bfhi(z.y));
	v_rcp_f32_e32 v29, v26
	s_nop 0
	v_mul_f32_e32 v26, v28, v29
	v_pk_mul_f32 v[24:25], v[24:25], v[26:27]
	s_nop 0
	v_cvt_pk_bf16_f32 v23, v24, v25
	v_add_u32_e32 v24, v44, v64
	ds_write_b64 v24, v[22:23]
	v_lshl_add_u64 v[22:23], v[38:39], 0, v[62:63]

;     DEV f32x4 xform(int r, int c, f32x4 v) const {
;     ...
;         const f32x4 s = *(const f32x4*)(scale + col);
	s_nop 0

; DEV float bflo(unsigned u) { return __uint_as_float(u << 16); }
; DEV float bfhi(unsigned u) { return __uint_as_float(u & 0xffff0000u); }
; DEV float silu_f(float x) { return x / (1.f + __expf(-x)); }
;     DEV f32x4 xform(int r, int c, f32x4 v) const {
;     ...
;         const uint2 z = *(const uint2*)(proj + (size_t)row * NPJ + C_ZB + col);
;         const f32x4 s = *(const f32x4*)(scale + col);
;         f32x4 o;
;         o[0] = v[0] * s[0] * silu_f(bflo(z.x)); o[1] = v[1] * s[1] * silu_f(bfhi(z.x));
;         o[2] = v[2] * s[2] * silu_f(bflo(z.y)); o[3] = v[3] * s[3] * silu_f(bfhi(z.y));
	s_waitcnt vmcnt(1)
	v_lshlrev_b32_e32 v30, 16, v230
	v_and_b32_e32 v26, 0xffff0000, v230
	v_mul_f32_e32 v28, 0xbfb8aa3b, v30
	s_waitcnt vmcnt(0)
	v_pk_mul_f32 v[18:19], v[18:19], v[212:213]
	v_mul_f32_e32 v22, 0xbfb8aa3b, v26
	v_exp_f32_e32 v28, v28
	v_exp_f32_e32 v29, v22
	v_pk_mul_f32 v[20:21], v[20:21], v[214:215]
	v_pk_add_f32 v[22:23], v[28:29], 1.0 op_sel_hi:[1,0]
	s_nop 0


; DEV float bflo(unsigned u) { return __uint_as_float(u << 16); }
; DEV float bfhi(unsigned u) { return __uint_as_float(u & 0xffff0000u); }
; DEV float silu_f(float x) { return x / (1.f + __expf(-x)); }
;     DEV f32x4 xform(int r, int c, f32x4 v) const {
;     ...
;         o[0] = v[0] * s[0] * silu_f(bflo(z.x)); o[1] = v[1] * s[1] * silu_f(bfhi(z.x));
;         o[2] = v[2] * s[2] * silu_f(bflo(z.y)); o[3] = v[3] * s[3] * silu_f(bfhi(z.y));
	s_nop 0


; DEV float bflo(unsigned u) { return __uint_as_float(u << 16); }
; DEV float bfhi(unsigned u) { return __uint_as_float(u & 0xffff0000u); }
; DEV float silu_f(float x) { return x / (1.f + __expf(-x)); }
;     DEV f32x4 xform(int r, int c, f32x4 v) const {
;     ...
;         o[0] = v[0] * s[0] * silu_f(bflo(z.x)); o[1] = v[1] * s[1] * silu_f(bfhi(z.x));
;         o[2] = v[2] * s[2] * silu_f(bflo(z.y)); o[3] = v[3] * s[3] * silu_f(bfhi(z.y));
	v_rcp_f32_e32 v24, v23
	s_nop 0
	v_mul_f32_e32 v23, v26, v24


; DEV float bflo(unsigned u) { return __uint_as_float(u << 16); }
; DEV float bfhi(unsigned u) { return __uint_as_float(u & 0xffff0000u); }
; DEV float silu_f(float x) { return x / (1.f + __expf(-x)); }
;     DEV f32x4 xform(int r, int c, f32x4 v) const {
;     ...
;         o[0] = v[0] * s[0] * silu_f(bflo(z.x)); o[1] = v[1] * s[1] * silu_f(bfhi(z.x));
;         o[2] = v[2] * s[2] * silu_f(bflo(z.y)); o[3] = v[3] * s[3] * silu_f(bfhi(z.y));
	s_nop 0


; DEV float bflo(unsigned u) { return __uint_as_float(u << 16); }
; DEV float bfhi(unsigned u) { return __uint_as_float(u & 0xffff0000u); }
; DEV float silu_f(float x) { return x / (1.f + __expf(-x)); }
;     DEV f32x4 xform(int r, int c, f32x4 v) const {
;     ...
;         f32x4 o;
;         o[0] = v[0] * s[0] * silu_f(bflo(z.x)); o[1] = v[1] * s[1] * silu_f(bfhi(z.x));
;         o[2] = v[2] * s[2] * silu_f(bflo(z.y)); o[3] = v[3] * s[3] * silu_f(bfhi(z.y));
	v_rcp_f32_e32 v24, v22
	s_nop 0
	v_mul_f32_e32 v22, v30, v24
	v_lshlrev_b32_e32 v24, 16, v231
	v_and_b32_e32 v25, 0xffff0000, v231
	v_pk_mul_f32 v[18:19], v[18:19], v[22:23]
	v_mul_f32_e32 v22, 0xbfb8aa3b, v24
	v_mul_f32_e32 v23, 0xbfb8aa3b, v25
	v_exp_f32_e32 v22, v22
	v_exp_f32_e32 v23, v23
	v_cvt_pk_bf16_f32 v18, v18, v19
	v_pk_add_f32 v[22:23], v[22:23], 1.0 op_sel_hi:[1,0]
	s_nop 0


; DEV float bflo(unsigned u) { return __uint_as_float(u << 16); }
; DEV float bfhi(unsigned u) { return __uint_as_float(u & 0xffff0000u); }
; DEV float silu_f(float x) { return x / (1.f + __expf(-x)); }
;     DEV f32x4 xform(int r, int c, f32x4 v) const {
;     ...
;         o[0] = v[0] * s[0] * silu_f(bflo(z.x)); o[1] = v[1] * s[1] * silu_f(bfhi(z.x));
;         o[2] = v[2] * s[2] * silu_f(bflo(z.y)); o[3] = v[3] * s[3] * silu_f(bfhi(z.y));
	s_nop 0


; DEV float bflo(unsigned u) { return __uint_as_float(u << 16); }
; DEV float bfhi(unsigned u) { return __uint_as_float(u & 0xffff0000u); }
; DEV float silu_f(float x) { return x / (1.f + __expf(-x)); }
;     DEV f32x4 xform(int r, int c, f32x4 v) const {
;     ...
;         o[0] = v[0] * s[0] * silu_f(bflo(z.x)); o[1] = v[1] * s[1] * silu_f(bfhi(z.x));
;         o[2] = v[2] * s[2] * silu_f(bflo(z.y)); o[3] = v[3] * s[3] * silu_f(bfhi(z.y));
	v_rcp_f32_e32 v26, v23
	s_nop 0
	v_mul_f32_e32 v23, v25, v26


; DEV float bflo(unsigned u) { return __uint_as_float(u << 16); }
; DEV float bfhi(unsigned u) { return __uint_as_float(u & 0xffff0000u); }
; DEV float silu_f(float x) { return x / (1.f + __expf(-x)); }
;     DEV f32x4 xform(int r, int c, f32x4 v) const {
;     ...
;         o[0] = v[0] * s[0] * silu_f(bflo(z.x)); o[1] = v[1] * s[1] * silu_f(bfhi(z.x));
;         o[2] = v[2] * s[2] * silu_f(bflo(z.y)); o[3] = v[3] * s[3] * silu_f(bfhi(z.y));
	s_nop 0


; DEV unsigned cvt_pk_bf16(float lo, float hi) { const f32x2_t v = {lo, hi}; const bf16x2_t b = __builtin_convertvector(v, bf16x2_t); return __builtin_bit_cast(unsigned, b); }
; DEV float bflo(unsigned u) { return __uint_as_float(u << 16); }
; DEV float bfhi(unsigned u) { return __uint_as_float(u & 0xffff0000u); }
; DEV float silu_f(float x) { return x / (1.f + __expf(-x)); }
; template <int WT, class Epi>
; DEV void gemm_tile(const bf16_t* __restrict__ A, int lda, const bf16_t* __restrict__ Bt, int ldb, int K, unsigned char* lds, const Epi& epi) {
;     ...
;                 const int row = wr * WT + mi * 16 + fr, col = wc * WT + ni * 16 + fq * 4;
;                 const f32x4 v = epi.xform(row, col, acc[mi][ni]);
;                 uint2 w; w.x = cvt_pk_bf16(v[0], v[1]); w.y = cvt_pk_bf16(v[2], v[3]);
;                 *(uint2*)(lds + row * RB + ((((col >> 3) ^ (row & (CPR - 1))) << 4) | (((col >> 2) & 1) << 3))) = w;
;     DEV f32x4 xform(int r, int c, f32x4 v) const {
;     ...
;         o[0] = v[0] * s[0] * silu_f(bflo(z.x)); o[1] = v[1] * s[1] * silu_f(bfhi(z.x));
;         o[2] = v[2] * s[2] * silu_f(bflo(z.y)); o[3] = v[3] * s[3] * silu_f(bfhi(z.y));
	v_rcp_f32_e32 v25, v22
	s_nop 0
	v_mul_f32_e32 v22, v24, v25
	v_pk_mul_f32 v[20:21], v[20:21], v[22:23]
	s_nop 0
	v_cvt_pk_bf16_f32 v19, v20, v21
	v_add_u32_e32 v20, v44, v58
	ds_write_b64 v20, v[18:19]
	v_or_b32_e32 v18, 48, v130
	v_lshl_add_u32 v28, v18, 8, s70
	v_add_u32_e32 v18, s81, v18
	v_mad_i64_i32 v[18:19], s[68:69], v18, s79, v[172:173]
	v_lshl_add_u64 v[22:23], v[18:19], 0, s[66:67]
	v_lshl_add_u64 v[18:19], v[22:23], 0, v[68:69]

;     DEV f32x4 xform(int r, int c, f32x4 v) const {
;     ...
;         const f32x4 s = *(const f32x4*)(scale + col);
	s_nop 0

; DEV float bflo(unsigned u) { return __uint_as_float(u << 16); }
; DEV float bfhi(unsigned u) { return __uint_as_float(u & 0xffff0000u); }
; DEV float silu_f(float x) { return x / (1.f + __expf(-x)); }
;     DEV f32x4 xform(int r, int c, f32x4 v) const {
;     ...
;         const f32x4 s = *(const f32x4*)(scale + col);
;         f32x4 o;
;         o[0] = v[0] * s[0] * silu_f(bflo(z.x)); o[1] = v[1] * s[1] * silu_f(bfhi(z.x));
;         o[2] = v[2] * s[2] * silu_f(bflo(z.y)); o[3] = v[3] * s[3] * silu_f(bfhi(z.y));
	s_waitcnt vmcnt(1)
	v_lshlrev_b32_e32 v29, 16, v232
	v_and_b32_e32 v24, 0xffff0000, v232
	v_mul_f32_e32 v26, 0xbfb8aa3b, v29
	s_waitcnt vmcnt(0)
	v_pk_mul_f32 v[14:15], v[14:15], v[194:195]
	v_mul_f32_e32 v18, 0xbfb8aa3b, v24
	v_exp_f32_e32 v26, v26
	v_exp_f32_e32 v27, v18
	v_pk_mul_f32 v[16:17], v[16:17], v[196:197]
	v_pk_add_f32 v[18:19], v[26:27], 1.0 op_sel_hi:[1,0]
	s_nop 0


; DEV float bflo(unsigned u) { return __uint_as_float(u << 16); }
; DEV float bfhi(unsigned u) { return __uint_as_float(u & 0xffff0000u); }
; DEV float silu_f(float x) { return x / (1.f + __expf(-x)); }
;     DEV f32x4 xform(int r, int c, f32x4 v) const {
;     ...
;         o[0] = v[0] * s[0] * silu_f(bflo(z.x)); o[1] = v[1] * s[1] * silu_f(bfhi(z.x));
;         o[2] = v[2] * s[2] * silu_f(bflo(z.y)); o[3] = v[3] * s[3] * silu_f(bfhi(z.y));
	s_nop 0


; DEV float bflo(unsigned u) { return __uint_as_float(u << 16); }
; DEV float bfhi(unsigned u) { return __uint_as_float(u & 0xffff0000u); }
; DEV float silu_f(float x) { return x / (1.f + __expf(-x)); }
;     DEV f32x4 xform(int r, int c, f32x4 v) const {
;     ...
;         o[0] = v[0] * s[0] * silu_f(bflo(z.x)); o[1] = v[1] * s[1] * silu_f(bfhi(z.x));
;         o[2] = v[2] * s[2] * silu_f(bflo(z.y)); o[3] = v[3] * s[3] * silu_f(bfhi(z.y));
	v_rcp_f32_e32 v20, v19
	s_nop 0
	v_mul_f32_e32 v19, v24, v20


; DEV float bflo(unsigned u) { return __uint_as_float(u << 16); }
; DEV float bfhi(unsigned u) { return __uint_as_float(u & 0xffff0000u); }
; DEV float silu_f(float x) { return x / (1.f + __expf(-x)); }
;     DEV f32x4 xform(int r, int c, f32x4 v) const {
;     ...
;         o[0] = v[0] * s[0] * silu_f(bflo(z.x)); o[1] = v[1] * s[1] * silu_f(bfhi(z.x));
;         o[2] = v[2] * s[2] * silu_f(bflo(z.y)); o[3] = v[3] * s[3] * silu_f(bfhi(z.y));
	s_nop 0


; DEV float bflo(unsigned u) { return __uint_as_float(u << 16); }
; DEV float bfhi(unsigned u) { return __uint_as_float(u & 0xffff0000u); }
; DEV float silu_f(float x) { return x / (1.f + __expf(-x)); }
;     DEV f32x4 xform(int r, int c, f32x4 v) const {
;     ...
;         f32x4 o;
;         o[0] = v[0] * s[0] * silu_f(bflo(z.x)); o[1] = v[1] * s[1] * silu_f(bfhi(z.x));
;         o[2] = v[2] * s[2] * silu_f(bflo(z.y)); o[3] = v[3] * s[3] * silu_f(bfhi(z.y));
	v_rcp_f32_e32 v20, v18
	s_nop 0
	v_mul_f32_e32 v18, v29, v20
	v_lshlrev_b32_e32 v20, 16, v233
	v_and_b32_e32 v21, 0xffff0000, v233
	v_pk_mul_f32 v[14:15], v[14:15], v[18:19]
	v_mul_f32_e32 v18, 0xbfb8aa3b, v20
	v_mul_f32_e32 v19, 0xbfb8aa3b, v21
	v_exp_f32_e32 v18, v18
	v_exp_f32_e32 v19, v19
	v_cvt_pk_bf16_f32 v14, v14, v15
	v_pk_add_f32 v[18:19], v[18:19], 1.0 op_sel_hi:[1,0]
	s_nop 0


; DEV float bflo(unsigned u) { return __uint_as_float(u << 16); }
; DEV float bfhi(unsigned u) { return __uint_as_float(u & 0xffff0000u); }
; DEV float silu_f(float x) { return x / (1.f + __expf(-x)); }
;     DEV f32x4 xform(int r, int c, f32x4 v) const {
;     ...
;         o[0] = v[0] * s[0] * silu_f(bflo(z.x)); o[1] = v[1] * s[1] * silu_f(bfhi(z.x));
;         o[2] = v[2] * s[2] * silu_f(bflo(z.y)); o[3] = v[3] * s[3] * silu_f(bfhi(z.y));
	s_nop 0


; DEV float bflo(unsigned u) { return __uint_as_float(u << 16); }
; DEV float bfhi(unsigned u) { return __uint_as_float(u & 0xffff0000u); }
; DEV float silu_f(float x) { return x / (1.f + __expf(-x)); }
;     DEV f32x4 xform(int r, int c, f32x4 v) const {
;     ...
;         o[0] = v[0] * s[0] * silu_f(bflo(z.x)); o[1] = v[1] * s[1] * silu_f(bfhi(z.x));
;         o[2] = v[2] * s[2] * silu_f(bflo(z.y)); o[3] = v[3] * s[3] * silu_f(bfhi(z.y));
	v_rcp_f32_e32 v24, v19
	s_nop 0
	v_mul_f32_e32 v19, v21, v24


; DEV float bflo(unsigned u) { return __uint_as_float(u << 16); }
; DEV float bfhi(unsigned u) { return __uint_as_float(u & 0xffff0000u); }
; DEV float silu_f(float x) { return x / (1.f + __expf(-x)); }
;     DEV f32x4 xform(int r, int c, f32x4 v) const {
;     ...
;         o[0] = v[0] * s[0] * silu_f(bflo(z.x)); o[1] = v[1] * s[1] * silu_f(bfhi(z.x));
;         o[2] = v[2] * s[2] * silu_f(bflo(z.y)); o[3] = v[3] * s[3] * silu_f(bfhi(z.y));
	s_nop 0


; DEV unsigned cvt_pk_bf16(float lo, float hi) { const f32x2_t v = {lo, hi}; const bf16x2_t b = __builtin_convertvector(v, bf16x2_t); return __builtin_bit_cast(unsigned, b); }
; DEV float bflo(unsigned u) { return __uint_as_float(u << 16); }
; DEV float bfhi(unsigned u) { return __uint_as_float(u & 0xffff0000u); }
; DEV float silu_f(float x) { return x / (1.f + __expf(-x)); }
; template <int WT, class Epi>
; DEV void gemm_tile(const bf16_t* __restrict__ A, int lda, const bf16_t* __restrict__ Bt, int ldb, int K, unsigned char* lds, const Epi& epi) {
;     ...
;                 const int row = wr * WT + mi * 16 + fr, col = wc * WT + ni * 16 + fq * 4;
;                 const f32x4 v = epi.xform(row, col, acc[mi][ni]);
;                 uint2 w; w.x = cvt_pk_bf16(v[0], v[1]); w.y = cvt_pk_bf16(v[2], v[3]);
;                 *(uint2*)(lds + row * RB + ((((col >> 3) ^ (row & (CPR - 1))) << 4) | (((col >> 2) & 1) << 3))) = w;
;     DEV f32x4 xform(int r, int c, f32x4 v) const {
;     ...
;         o[0] = v[0] * s[0] * silu_f(bflo(z.x)); o[1] = v[1] * s[1] * silu_f(bfhi(z.x));
;         o[2] = v[2] * s[2] * silu_f(bflo(z.y)); o[3] = v[3] * s[3] * silu_f(bfhi(z.y));
	v_rcp_f32_e32 v21, v18
	s_nop 0
	v_mul_f32_e32 v18, v20, v21
	v_pk_mul_f32 v[16:17], v[16:17], v[18:19]
	s_nop 0
	v_cvt_pk_bf16_f32 v15, v16, v17
	v_add_u32_e32 v16, v28, v76
	ds_write_b64 v16, v[14:15]
	v_lshl_add_u64 v[14:15], v[22:23], 0, v[72:73]

;     DEV f32x4 xform(int r, int c, f32x4 v) const {
;     ...
;         const f32x4 s = *(const f32x4*)(scale + col);
	s_nop 0

; DEV float bflo(unsigned u) { return __uint_as_float(u << 16); }
; DEV float bfhi(unsigned u) { return __uint_as_float(u & 0xffff0000u); }
; DEV float silu_f(float x) { return x / (1.f + __expf(-x)); }
;     DEV f32x4 xform(int r, int c, f32x4 v) const {
;     ...
;         const f32x4 s = *(const f32x4*)(scale + col);
;         f32x4 o;
;         o[0] = v[0] * s[0] * silu_f(bflo(z.x)); o[1] = v[1] * s[1] * silu_f(bfhi(z.x));
;         o[2] = v[2] * s[2] * silu_f(bflo(z.y)); o[3] = v[3] * s[3] * silu_f(bfhi(z.y));
	s_waitcnt vmcnt(1)
	v_lshlrev_b32_e32 v24, 16, v234
	v_and_b32_e32 v18, 0xffff0000, v234
	v_mul_f32_e32 v20, 0xbfb8aa3b, v24
	s_waitcnt vmcnt(0)
	v_pk_mul_f32 v[10:11], v[10:11], v[200:201]
	v_mul_f32_e32 v14, 0xbfb8aa3b, v18
	v_exp_f32_e32 v20, v20
	v_exp_f32_e32 v21, v14
	v_pk_mul_f32 v[12:13], v[12:13], v[202:203]
	v_pk_add_f32 v[14:15], v[20:21], 1.0 op_sel_hi:[1,0]
	s_nop 0


; DEV float bflo(unsigned u) { return __uint_as_float(u << 16); }
; DEV float bfhi(unsigned u) { return __uint_as_float(u & 0xffff0000u); }
; DEV float silu_f(float x) { return x / (1.f + __expf(-x)); }
;     DEV f32x4 xform(int r, int c, f32x4 v) const {
;     ...
;         o[0] = v[0] * s[0] * silu_f(bflo(z.x)); o[1] = v[1] * s[1] * silu_f(bfhi(z.x));
;         o[2] = v[2] * s[2] * silu_f(bflo(z.y)); o[3] = v[3] * s[3] * silu_f(bfhi(z.y));
	s_nop 0


; DEV float bflo(unsigned u) { return __uint_as_float(u << 16); }
; DEV float bfhi(unsigned u) { return __uint_as_float(u & 0xffff0000u); }
; DEV float silu_f(float x) { return x / (1.f + __expf(-x)); }
;     DEV f32x4 xform(int r, int c, f32x4 v) const {
;     ...
;         o[0] = v[0] * s[0] * silu_f(bflo(z.x)); o[1] = v[1] * s[1] * silu_f(bfhi(z.x));
;         o[2] = v[2] * s[2] * silu_f(bflo(z.y)); o[3] = v[3] * s[3] * silu_f(bfhi(z.y));
	v_rcp_f32_e32 v16, v15
	s_nop 0
	v_mul_f32_e32 v15, v18, v16


; DEV float bflo(unsigned u) { return __uint_as_float(u << 16); }
; DEV float bfhi(unsigned u) { return __uint_as_float(u & 0xffff0000u); }
; DEV float silu_f(float x) { return x / (1.f + __expf(-x)); }
;     DEV f32x4 xform(int r, int c, f32x4 v) const {
;     ...
;         o[0] = v[0] * s[0] * silu_f(bflo(z.x)); o[1] = v[1] * s[1] * silu_f(bfhi(z.x));
;         o[2] = v[2] * s[2] * silu_f(bflo(z.y)); o[3] = v[3] * s[3] * silu_f(bfhi(z.y));
	s_nop 0


; DEV float bflo(unsigned u) { return __uint_as_float(u << 16); }
; DEV float bfhi(unsigned u) { return __uint_as_float(u & 0xffff0000u); }
; DEV float silu_f(float x) { return x / (1.f + __expf(-x)); }
;     DEV f32x4 xform(int r, int c, f32x4 v) const {
;     ...
;         f32x4 o;
;         o[0] = v[0] * s[0] * silu_f(bflo(z.x)); o[1] = v[1] * s[1] * silu_f(bfhi(z.x));
;         o[2] = v[2] * s[2] * silu_f(bflo(z.y)); o[3] = v[3] * s[3] * silu_f(bfhi(z.y));
	v_rcp_f32_e32 v16, v14
	s_nop 0
	v_mul_f32_e32 v14, v24, v16
	v_lshlrev_b32_e32 v16, 16, v235
	v_and_b32_e32 v17, 0xffff0000, v235
	v_pk_mul_f32 v[10:11], v[10:11], v[14:15]
	v_mul_f32_e32 v14, 0xbfb8aa3b, v16
	v_mul_f32_e32 v15, 0xbfb8aa3b, v17
	v_exp_f32_e32 v14, v14
	v_exp_f32_e32 v15, v15
	v_cvt_pk_bf16_f32 v10, v10, v11
	v_pk_add_f32 v[14:15], v[14:15], 1.0 op_sel_hi:[1,0]
	s_nop 0


; DEV float bflo(unsigned u) { return __uint_as_float(u << 16); }
; DEV float bfhi(unsigned u) { return __uint_as_float(u & 0xffff0000u); }
; DEV float silu_f(float x) { return x / (1.f + __expf(-x)); }
;     DEV f32x4 xform(int r, int c, f32x4 v) const {
;     ...
;         o[0] = v[0] * s[0] * silu_f(bflo(z.x)); o[1] = v[1] * s[1] * silu_f(bfhi(z.x));
;         o[2] = v[2] * s[2] * silu_f(bflo(z.y)); o[3] = v[3] * s[3] * silu_f(bfhi(z.y));
	s_nop 0


; DEV float bflo(unsigned u) { return __uint_as_float(u << 16); }
; DEV float bfhi(unsigned u) { return __uint_as_float(u & 0xffff0000u); }
; DEV float silu_f(float x) { return x / (1.f + __expf(-x)); }
;     DEV f32x4 xform(int r, int c, f32x4 v) const {
;     ...
;         o[0] = v[0] * s[0] * silu_f(bflo(z.x)); o[1] = v[1] * s[1] * silu_f(bfhi(z.x));
;         o[2] = v[2] * s[2] * silu_f(bflo(z.y)); o[3] = v[3] * s[3] * silu_f(bfhi(z.y));
	v_rcp_f32_e32 v18, v15
	s_nop 0
	v_mul_f32_e32 v15, v17, v18


; DEV float bflo(unsigned u) { return __uint_as_float(u << 16); }
; DEV float bfhi(unsigned u) { return __uint_as_float(u & 0xffff0000u); }
; DEV float silu_f(float x) { return x / (1.f + __expf(-x)); }
;     DEV f32x4 xform(int r, int c, f32x4 v) const {
;     ...
;         o[0] = v[0] * s[0] * silu_f(bflo(z.x)); o[1] = v[1] * s[1] * silu_f(bfhi(z.x));
;         o[2] = v[2] * s[2] * silu_f(bflo(z.y)); o[3] = v[3] * s[3] * silu_f(bfhi(z.y));
	s_nop 0


; DEV unsigned cvt_pk_bf16(float lo, float hi) { const f32x2_t v = {lo, hi}; const bf16x2_t b = __builtin_convertvector(v, bf16x2_t); return __builtin_bit_cast(unsigned, b); }
; DEV float bflo(unsigned u) { return __uint_as_float(u << 16); }
; DEV float bfhi(unsigned u) { return __uint_as_float(u & 0xffff0000u); }
; DEV float silu_f(float x) { return x / (1.f + __expf(-x)); }
; template <int WT, class Epi>
; DEV void gemm_tile(const bf16_t* __restrict__ A, int lda, const bf16_t* __restrict__ Bt, int ldb, int K, unsigned char* lds, const Epi& epi) {
;     ...
;                 const int row = wr * WT + mi * 16 + fr, col = wc * WT + ni * 16 + fq * 4;
;                 const f32x4 v = epi.xform(row, col, acc[mi][ni]);
;                 uint2 w; w.x = cvt_pk_bf16(v[0], v[1]); w.y = cvt_pk_bf16(v[2], v[3]);
;                 *(uint2*)(lds + row * RB + ((((col >> 3) ^ (row & (CPR - 1))) << 4) | (((col >> 2) & 1) << 3))) = w;
;     DEV f32x4 xform(int r, int c, f32x4 v) const {
;     ...
;         o[0] = v[0] * s[0] * silu_f(bflo(z.x)); o[1] = v[1] * s[1] * silu_f(bfhi(z.x));
;         o[2] = v[2] * s[2] * silu_f(bflo(z.y)); o[3] = v[3] * s[3] * silu_f(bfhi(z.y));
	v_rcp_f32_e32 v17, v14
	s_nop 0
	v_mul_f32_e32 v14, v16, v17
	v_pk_mul_f32 v[12:13], v[12:13], v[14:15]
	s_nop 0
	v_cvt_pk_bf16_f32 v11, v12, v13
	v_add_u32_e32 v12, v28, v77
	ds_write_b64 v12, v[10:11]
	v_lshl_add_u64 v[10:11], v[22:23], 0, v[74:75]

;     DEV f32x4 xform(int r, int c, f32x4 v) const {
;     ...
;         const f32x4 s = *(const f32x4*)(scale + col);
	s_nop 0

; DEV float bflo(unsigned u) { return __uint_as_float(u << 16); }
; DEV float bfhi(unsigned u) { return __uint_as_float(u & 0xffff0000u); }
; DEV float silu_f(float x) { return x / (1.f + __expf(-x)); }
;     DEV f32x4 xform(int r, int c, f32x4 v) const {
;     ...
;         const f32x4 s = *(const f32x4*)(scale + col);
;         f32x4 o;
;         o[0] = v[0] * s[0] * silu_f(bflo(z.x)); o[1] = v[1] * s[1] * silu_f(bfhi(z.x));
;         o[2] = v[2] * s[2] * silu_f(bflo(z.y)); o[3] = v[3] * s[3] * silu_f(bfhi(z.y));
	s_waitcnt vmcnt(1)
	v_lshlrev_b32_e32 v18, 16, v236
	v_and_b32_e32 v14, 0xffff0000, v236
	v_mul_f32_e32 v16, 0xbfb8aa3b, v18
	s_waitcnt vmcnt(0)
	v_pk_mul_f32 v[6:7], v[6:7], v[206:207]
	v_mul_f32_e32 v10, 0xbfb8aa3b, v14
	v_exp_f32_e32 v16, v16
	v_exp_f32_e32 v17, v10
	v_pk_mul_f32 v[8:9], v[8:9], v[208:209]
	v_pk_add_f32 v[10:11], v[16:17], 1.0 op_sel_hi:[1,0]
	s_nop 0


; DEV float bflo(unsigned u) { return __uint_as_float(u << 16); }
; DEV float bfhi(unsigned u) { return __uint_as_float(u & 0xffff0000u); }
; DEV float silu_f(float x) { return x / (1.f + __expf(-x)); }
;     DEV f32x4 xform(int r, int c, f32x4 v) const {
;     ...
;         o[0] = v[0] * s[0] * silu_f(bflo(z.x)); o[1] = v[1] * s[1] * silu_f(bfhi(z.x));
;         o[2] = v[2] * s[2] * silu_f(bflo(z.y)); o[3] = v[3] * s[3] * silu_f(bfhi(z.y));
	s_nop 0


; DEV float bflo(unsigned u) { return __uint_as_float(u << 16); }
; DEV float bfhi(unsigned u) { return __uint_as_float(u & 0xffff0000u); }
; DEV float silu_f(float x) { return x / (1.f + __expf(-x)); }
;     DEV f32x4 xform(int r, int c, f32x4 v) const {
;     ...
;         o[0] = v[0] * s[0] * silu_f(bflo(z.x)); o[1] = v[1] * s[1] * silu_f(bfhi(z.x));
;         o[2] = v[2] * s[2] * silu_f(bflo(z.y)); o[3] = v[3] * s[3] * silu_f(bfhi(z.y));
	v_rcp_f32_e32 v12, v11
	s_nop 0
	v_mul_f32_e32 v11, v14, v12


; DEV float bflo(unsigned u) { return __uint_as_float(u << 16); }
; DEV float bfhi(unsigned u) { return __uint_as_float(u & 0xffff0000u); }
; DEV float silu_f(float x) { return x / (1.f + __expf(-x)); }
;     DEV f32x4 xform(int r, int c, f32x4 v) const {
;     ...
;         o[0] = v[0] * s[0] * silu_f(bflo(z.x)); o[1] = v[1] * s[1] * silu_f(bfhi(z.x));
;         o[2] = v[2] * s[2] * silu_f(bflo(z.y)); o[3] = v[3] * s[3] * silu_f(bfhi(z.y));
	s_nop 0


; DEV float bflo(unsigned u) { return __uint_as_float(u << 16); }
; DEV float bfhi(unsigned u) { return __uint_as_float(u & 0xffff0000u); }
; DEV float silu_f(float x) { return x / (1.f + __expf(-x)); }
;     DEV f32x4 xform(int r, int c, f32x4 v) const {
;     ...
;         f32x4 o;
;         o[0] = v[0] * s[0] * silu_f(bflo(z.x)); o[1] = v[1] * s[1] * silu_f(bfhi(z.x));
;         o[2] = v[2] * s[2] * silu_f(bflo(z.y)); o[3] = v[3] * s[3] * silu_f(bfhi(z.y));
	v_rcp_f32_e32 v12, v10
	s_nop 0
	v_mul_f32_e32 v10, v18, v12
	v_lshlrev_b32_e32 v12, 16, v237
	v_and_b32_e32 v13, 0xffff0000, v237
	v_pk_mul_f32 v[6:7], v[6:7], v[10:11]
	v_mul_f32_e32 v10, 0xbfb8aa3b, v12
	v_mul_f32_e32 v11, 0xbfb8aa3b, v13
	v_exp_f32_e32 v10, v10
	v_exp_f32_e32 v11, v11
	v_cvt_pk_bf16_f32 v6, v6, v7
	v_pk_add_f32 v[10:11], v[10:11], 1.0 op_sel_hi:[1,0]
	s_nop 0


; DEV float bflo(unsigned u) { return __uint_as_float(u << 16); }
; DEV float bfhi(unsigned u) { return __uint_as_float(u & 0xffff0000u); }
; DEV float silu_f(float x) { return x / (1.f + __expf(-x)); }
;     DEV f32x4 xform(int r, int c, f32x4 v) const {
;     ...
;         o[0] = v[0] * s[0] * silu_f(bflo(z.x)); o[1] = v[1] * s[1] * silu_f(bfhi(z.x));
;         o[2] = v[2] * s[2] * silu_f(bflo(z.y)); o[3] = v[3] * s[3] * silu_f(bfhi(z.y));
	s_nop 0


; DEV float bflo(unsigned u) { return __uint_as_float(u << 16); }
; DEV float bfhi(unsigned u) { return __uint_as_float(u & 0xffff0000u); }
; DEV float silu_f(float x) { return x / (1.f + __expf(-x)); }
;     DEV f32x4 xform(int r, int c, f32x4 v) const {
;     ...
;         o[0] = v[0] * s[0] * silu_f(bflo(z.x)); o[1] = v[1] * s[1] * silu_f(bfhi(z.x));
;         o[2] = v[2] * s[2] * silu_f(bflo(z.y)); o[3] = v[3] * s[3] * silu_f(bfhi(z.y));
	v_rcp_f32_e32 v14, v11
	s_nop 0
	v_mul_f32_e32 v11, v13, v14


; DEV float bflo(unsigned u) { return __uint_as_float(u << 16); }
; DEV float bfhi(unsigned u) { return __uint_as_float(u & 0xffff0000u); }
; DEV float silu_f(float x) { return x / (1.f + __expf(-x)); }
;     DEV f32x4 xform(int r, int c, f32x4 v) const {
;     ...
;         o[0] = v[0] * s[0] * silu_f(bflo(z.x)); o[1] = v[1] * s[1] * silu_f(bfhi(z.x));
;         o[2] = v[2] * s[2] * silu_f(bflo(z.y)); o[3] = v[3] * s[3] * silu_f(bfhi(z.y));
	s_nop 0


; DEV unsigned cvt_pk_bf16(float lo, float hi) { const f32x2_t v = {lo, hi}; const bf16x2_t b = __builtin_convertvector(v, bf16x2_t); return __builtin_bit_cast(unsigned, b); }
; DEV float bflo(unsigned u) { return __uint_as_float(u << 16); }
; DEV float bfhi(unsigned u) { return __uint_as_float(u & 0xffff0000u); }
; DEV float silu_f(float x) { return x / (1.f + __expf(-x)); }
; template <int WT, class Epi>
; DEV void gemm_tile(const bf16_t* __restrict__ A, int lda, const bf16_t* __restrict__ Bt, int ldb, int K, unsigned char* lds, const Epi& epi) {
;     ...
;                 const int row = wr * WT + mi * 16 + fr, col = wc * WT + ni * 16 + fq * 4;
;                 const f32x4 v = epi.xform(row, col, acc[mi][ni]);
;                 uint2 w; w.x = cvt_pk_bf16(v[0], v[1]); w.y = cvt_pk_bf16(v[2], v[3]);
;                 *(uint2*)(lds + row * RB + ((((col >> 3) ^ (row & (CPR - 1))) << 4) | (((col >> 2) & 1) << 3))) = w;
;     DEV f32x4 xform(int r, int c, f32x4 v) const {
;     ...
;         o[0] = v[0] * s[0] * silu_f(bflo(z.x)); o[1] = v[1] * s[1] * silu_f(bfhi(z.x));
;         o[2] = v[2] * s[2] * silu_f(bflo(z.y)); o[3] = v[3] * s[3] * silu_f(bfhi(z.y));
	v_rcp_f32_e32 v13, v10
	s_nop 0
	v_mul_f32_e32 v10, v12, v13
	v_pk_mul_f32 v[8:9], v[8:9], v[10:11]
	s_nop 0
	v_cvt_pk_bf16_f32 v7, v8, v9
	v_add_u32_e32 v8, v28, v64
	ds_write_b64 v8, v[6:7]
	v_lshl_add_u64 v[6:7], v[22:23], 0, v[62:63]

;     DEV f32x4 xform(int r, int c, f32x4 v) const {
;     ...
;         const f32x4 s = *(const f32x4*)(scale + col);
	s_nop 0

; DEV float bflo(unsigned u) { return __uint_as_float(u << 16); }
; DEV float bfhi(unsigned u) { return __uint_as_float(u & 0xffff0000u); }
; DEV float silu_f(float x) { return x / (1.f + __expf(-x)); }
;     DEV f32x4 xform(int r, int c, f32x4 v) const {
;     ...
;         const f32x4 s = *(const f32x4*)(scale + col);
;         f32x4 o;
;         o[0] = v[0] * s[0] * silu_f(bflo(z.x)); o[1] = v[1] * s[1] * silu_f(bfhi(z.x));
;         o[2] = v[2] * s[2] * silu_f(bflo(z.y)); o[3] = v[3] * s[3] * silu_f(bfhi(z.y));
	s_waitcnt vmcnt(1)
	v_lshlrev_b32_e32 v14, 16, v238
	v_and_b32_e32 v10, 0xffff0000, v238
	v_mul_f32_e32 v12, 0xbfb8aa3b, v14
	s_waitcnt vmcnt(0)
	v_pk_mul_f32 v[2:3], v[2:3], v[212:213]
	v_mul_f32_e32 v6, 0xbfb8aa3b, v10
	v_exp_f32_e32 v12, v12
	v_exp_f32_e32 v13, v6
	v_pk_mul_f32 v[4:5], v[4:5], v[214:215]
	v_pk_add_f32 v[6:7], v[12:13], 1.0 op_sel_hi:[1,0]
	s_nop 0


; DEV float bflo(unsigned u) { return __uint_as_float(u << 16); }
; DEV float bfhi(unsigned u) { return __uint_as_float(u & 0xffff0000u); }
; DEV float silu_f(float x) { return x / (1.f + __expf(-x)); }
;     DEV f32x4 xform(int r, int c, f32x4 v) const {
;     ...
;         o[0] = v[0] * s[0] * silu_f(bflo(z.x)); o[1] = v[1] * s[1] * silu_f(bfhi(z.x));
;         o[2] = v[2] * s[2] * silu_f(bflo(z.y)); o[3] = v[3] * s[3] * silu_f(bfhi(z.y));
	s_nop 0


; DEV float bflo(unsigned u) { return __uint_as_float(u << 16); }
; DEV float bfhi(unsigned u) { return __uint_as_float(u & 0xffff0000u); }
; DEV float silu_f(float x) { return x / (1.f + __expf(-x)); }
;     DEV f32x4 xform(int r, int c, f32x4 v) const {
;     ...
;         o[0] = v[0] * s[0] * silu_f(bflo(z.x)); o[1] = v[1] * s[1] * silu_f(bfhi(z.x));
;         o[2] = v[2] * s[2] * silu_f(bflo(z.y)); o[3] = v[3] * s[3] * silu_f(bfhi(z.y));
	v_rcp_f32_e32 v8, v7
	s_nop 0
	v_mul_f32_e32 v7, v10, v8


; DEV float bflo(unsigned u) { return __uint_as_float(u << 16); }
; DEV float bfhi(unsigned u) { return __uint_as_float(u & 0xffff0000u); }
; DEV float silu_f(float x) { return x / (1.f + __expf(-x)); }
;     DEV f32x4 xform(int r, int c, f32x4 v) const {
;     ...
;         o[0] = v[0] * s[0] * silu_f(bflo(z.x)); o[1] = v[1] * s[1] * silu_f(bfhi(z.x));
;         o[2] = v[2] * s[2] * silu_f(bflo(z.y)); o[3] = v[3] * s[3] * silu_f(bfhi(z.y));
	s_nop 0


; DEV float bflo(unsigned u) { return __uint_as_float(u << 16); }
; DEV float bfhi(unsigned u) { return __uint_as_float(u & 0xffff0000u); }
; DEV float silu_f(float x) { return x / (1.f + __expf(-x)); }
;     DEV f32x4 xform(int r, int c, f32x4 v) const {
;     ...
;         f32x4 o;
;         o[0] = v[0] * s[0] * silu_f(bflo(z.x)); o[1] = v[1] * s[1] * silu_f(bfhi(z.x));
;         o[2] = v[2] * s[2] * silu_f(bflo(z.y)); o[3] = v[3] * s[3] * silu_f(bfhi(z.y));
	v_rcp_f32_e32 v8, v6
	s_nop 0
	v_mul_f32_e32 v6, v14, v8
	v_lshlrev_b32_e32 v8, 16, v239
	v_and_b32_e32 v9, 0xffff0000, v239
	v_pk_mul_f32 v[2:3], v[2:3], v[6:7]
	v_mul_f32_e32 v6, 0xbfb8aa3b, v8
	v_mul_f32_e32 v7, 0xbfb8aa3b, v9
	v_exp_f32_e32 v6, v6
	v_exp_f32_e32 v7, v7
	v_cvt_pk_bf16_f32 v2, v2, v3
	v_pk_add_f32 v[6:7], v[6:7], 1.0 op_sel_hi:[1,0]
	s_nop 0


; DEV float bflo(unsigned u) { return __uint_as_float(u << 16); }
; DEV float bfhi(unsigned u) { return __uint_as_float(u & 0xffff0000u); }
; DEV float silu_f(float x) { return x / (1.f + __expf(-x)); }
;     DEV f32x4 xform(int r, int c, f32x4 v) const {
;     ...
;         o[0] = v[0] * s[0] * silu_f(bflo(z.x)); o[1] = v[1] * s[1] * silu_f(bfhi(z.x));
;         o[2] = v[2] * s[2] * silu_f(bflo(z.y)); o[3] = v[3] * s[3] * silu_f(bfhi(z.y));
	s_nop 0


; DEV float bflo(unsigned u) { return __uint_as_float(u << 16); }
; DEV float bfhi(unsigned u) { return __uint_as_float(u & 0xffff0000u); }
; DEV float silu_f(float x) { return x / (1.f + __expf(-x)); }
;     DEV f32x4 xform(int r, int c, f32x4 v) const {
;     ...
;         o[0] = v[0] * s[0] * silu_f(bflo(z.x)); o[1] = v[1] * s[1] * silu_f(bfhi(z.x));
;         o[2] = v[2] * s[2] * silu_f(bflo(z.y)); o[3] = v[3] * s[3] * silu_f(bfhi(z.y));
	v_rcp_f32_e32 v10, v7
	s_nop 0
	v_mul_f32_e32 v7, v9, v10


; DEV float bflo(unsigned u) { return __uint_as_float(u << 16); }
; DEV float bfhi(unsigned u) { return __uint_as_float(u & 0xffff0000u); }
; DEV float silu_f(float x) { return x / (1.f + __expf(-x)); }
;     DEV f32x4 xform(int r, int c, f32x4 v) const {
;     ...
;         o[0] = v[0] * s[0] * silu_f(bflo(z.x)); o[1] = v[1] * s[1] * silu_f(bfhi(z.x));
;         o[2] = v[2] * s[2] * silu_f(bflo(z.y)); o[3] = v[3] * s[3] * silu_f(bfhi(z.y));
	s_nop 0


; DEV unsigned cvt_pk_bf16(float lo, float hi) { const f32x2_t v = {lo, hi}; const bf16x2_t b = __builtin_convertvector(v, bf16x2_t); return __builtin_bit_cast(unsigned, b); }
; template <int WT, class Epi>
; DEV void gemm_tile(const bf16_t* __restrict__ A, int lda, const bf16_t* __restrict__ Bt, int ldb, int K, unsigned char* lds, const Epi& epi) {
;     ...
;                 uint2 w; w.x = cvt_pk_bf16(v[0], v[1]); w.y = cvt_pk_bf16(v[2], v[3]);
;                 *(uint2*)(lds + row * RB + ((((col >> 3) ^ (row & (CPR - 1))) << 4) | (((col >> 2) & 1) << 3))) = w;
;             }
;         __syncthreads();
; #pragma unroll
;         for (int i = 0; i < (2 * WT * CPR) / 256; ++i) {
;             const int idx = tid + 256 * i, row = idx / CPR, cp = idx % CPR, c = cp ^ (row & (CPR - 1));
;             const uint4 d = *(const uint4*)(lds + row * RB + (cp << 4));
;             *(uint4*)(epi.obase + (size_t)row * epi.old + c * 8) = epi.finish(row, c * 8, d);
;         }
	v_rcp_f32_e32 v9, v6
	s_nop 0
	v_mul_f32_e32 v6, v8, v9
	v_pk_mul_f32 v[4:5], v[4:5], v[6:7]
	s_nop 0
	v_cvt_pk_bf16_f32 v3, v4, v5
	v_add_u32_e32 v4, v28, v58
	ds_write_b64 v4, v[2:3]
	v_ashrrev_i32_e32 v2, 31, v137
	v_lshrrev_b32_e32 v2, 28, v2
	v_add_u32_e32 v2, v137, v2
	v_ashrrev_i32_e32 v3, 4, v2
	v_and_b32_e32 v2, -16, v2
	v_sub_u32_e32 v2, v137, v2
	v_bitop3_b32 v4, v3, v2, 15 bitop3:0x6c
	v_lshlrev_b32_e32 v5, 8, v3
	v_lshlrev_b32_e32 v2, 4, v2
	v_add3_u32 v8, s70, v5, v2
	v_lshlrev_b32_e32 v2, 3, v4
	v_mad_i64_i32 v[4:5], s[68:69], v3, s80, v[132:133]
	v_ashrrev_i32_e32 v3, 31, v2
	s_waitcnt lgkmcnt(0)
	s_barrier
	v_lshl_add_u64 v[6:7], v[2:3], 1, v[4:5]
	ds_read_b128 v[2:5], v8
	s_waitcnt lgkmcnt(0)
	global_store_dwordx4 v[6:7], v[2:5], off offset:2048
	s_nop 1
	v_add_u32_e32 v2, 0x100, v137
	v_ashrrev_i32_e32 v3, 31, v2
	v_lshrrev_b32_e32 v3, 28, v3
	v_add_u32_e32 v3, v2, v3
	v_ashrrev_i32_e32 v4, 4, v3
	v_and_b32_e32 v3, -16, v3
	v_sub_u32_e32 v2, v2, v3
	v_bitop3_b32 v3, v4, v2, 15 bitop3:0x6c
	v_lshlrev_b32_e32 v5, 8, v4
	v_lshlrev_b32_e32 v2, 4, v2
	v_add3_u32 v8, s70, v5, v2
	v_lshlrev_b32_e32 v2, 3, v3
	v_mad_i64_i32 v[4:5], s[68:69], v4, s80, v[132:133]
	v_ashrrev_i32_e32 v3, 31, v2
	v_lshl_add_u64 v[6:7], v[2:3], 1, v[4:5]
	ds_read_b128 v[2:5], v8
	s_waitcnt lgkmcnt(0)
	global_store_dwordx4 v[6:7], v[2:5], off offset:2048
	s_nop 1
	v_add_u32_e32 v2, 0x200, v137
	v_ashrrev_i32_e32 v3, 31, v2
	v_lshrrev_b32_e32 v3, 28, v3
	v_add_u32_e32 v3, v2, v3
	v_ashrrev_i32_e32 v4, 4, v3
	v_and_b32_e32 v3, -16, v3
	v_sub_u32_e32 v2, v2, v3
	v_bitop3_b32 v3, v4, v2, 15 bitop3:0x6c
	v_lshlrev_b32_e32 v5, 8, v4
	v_lshlrev_b32_e32 v2, 4, v2
	v_add3_u32 v8, s70, v5, v2
	v_lshlrev_b32_e32 v2, 3, v3
	v_mad_i64_i32 v[4:5], s[68:69], v4, s80, v[132:133]
	v_ashrrev_i32_e32 v3, 31, v2
	v_lshl_add_u64 v[6:7], v[2:3], 1, v[4:5]
	ds_read_b128 v[2:5], v8
	s_waitcnt lgkmcnt(0)
	global_store_dwordx4 v[6:7], v[2:5], off offset:2048
	s_nop 1
	v_add_u32_e32 v2, 0x300, v137
	v_ashrrev_i32_e32 v3, 31, v2
	v_lshrrev_b32_e32 v3, 28, v3
	v_add_u32_e32 v3, v2, v3
	v_ashrrev_i32_e32 v4, 4, v3
	v_and_b32_e32 v3, -16, v3
	v_sub_u32_e32 v2, v2, v3
	v_bitop3_b32 v3, v4, v2, 15 bitop3:0x6c
	v_lshlrev_b32_e32 v5, 8, v4
	v_lshlrev_b32_e32 v2, 4, v2
	v_add3_u32 v8, s70, v5, v2
	v_lshlrev_b32_e32 v2, 3, v3
	v_mad_i64_i32 v[4:5], s[68:69], v4, s80, v[132:133]
	v_ashrrev_i32_e32 v3, 31, v2
	v_lshl_add_u64 v[6:7], v[2:3], 1, v[4:5]
	ds_read_b128 v[2:5], v8
	s_waitcnt lgkmcnt(0)
	global_store_dwordx4 v[6:7], v[2:5], off offset:2048
	s_nop 1
	v_add_u32_e32 v2, 0x400, v137
	v_ashrrev_i32_e32 v3, 31, v2
	v_lshrrev_b32_e32 v3, 28, v3
	v_add_u32_e32 v3, v2, v3
	v_ashrrev_i32_e32 v4, 4, v3
	v_and_b32_e32 v3, -16, v3
	v_sub_u32_e32 v2, v2, v3
	v_bitop3_b32 v3, v4, v2, 15 bitop3:0x6c
	v_lshlrev_b32_e32 v5, 8, v4
	v_lshlrev_b32_e32 v2, 4, v2
	v_add3_u32 v8, s70, v5, v2
	v_lshlrev_b32_e32 v2, 3, v3
	v_mad_i64_i32 v[4:5], s[68:69], v4, s80, v[132:133]
	v_ashrrev_i32_e32 v3, 31, v2
	v_lshl_add_u64 v[6:7], v[2:3], 1, v[4:5]
	ds_read_b128 v[2:5], v8
	s_waitcnt lgkmcnt(0)
	global_store_dwordx4 v[6:7], v[2:5], off offset:2048
	s_nop 1
	v_add_u32_e32 v2, 0x500, v137
	v_ashrrev_i32_e32 v3, 31, v2
	v_lshrrev_b32_e32 v3, 28, v3
	v_add_u32_e32 v3, v2, v3
	v_ashrrev_i32_e32 v4, 4, v3
	v_and_b32_e32 v3, -16, v3
	v_sub_u32_e32 v2, v2, v3
	v_bitop3_b32 v3, v4, v2, 15 bitop3:0x6c
	v_lshlrev_b32_e32 v5, 8, v4
	v_lshlrev_b32_e32 v2, 4, v2
	v_add3_u32 v8, s70, v5, v2
	v_lshlrev_b32_e32 v2, 3, v3
	v_mad_i64_i32 v[4:5], s[68:69], v4, s80, v[132:133]
	v_ashrrev_i32_e32 v3, 31, v2
	v_lshl_add_u64 v[6:7], v[2:3], 1, v[4:5]
	ds_read_b128 v[2:5], v8
	s_waitcnt lgkmcnt(0)
	global_store_dwordx4 v[6:7], v[2:5], off offset:2048
	s_nop 1
	v_add_u32_e32 v2, 0x600, v137
	v_ashrrev_i32_e32 v3, 31, v2
	v_lshrrev_b32_e32 v3, 28, v3
	v_add_u32_e32 v3, v2, v3
	v_ashrrev_i32_e32 v4, 4, v3
	v_and_b32_e32 v3, -16, v3
	v_sub_u32_e32 v2, v2, v3
	v_bitop3_b32 v3, v4, v2, 15 bitop3:0x6c
	v_lshlrev_b32_e32 v5, 8, v4
	v_lshlrev_b32_e32 v2, 4, v2
	v_add3_u32 v8, s70, v5, v2
	v_lshlrev_b32_e32 v2, 3, v3
	v_mad_i64_i32 v[4:5], s[68:69], v4, s80, v[132:133]
	v_ashrrev_i32_e32 v3, 31, v2
	v_lshl_add_u64 v[6:7], v[2:3], 1, v[4:5]
	ds_read_b128 v[2:5], v8
	s_waitcnt lgkmcnt(0)
	global_store_dwordx4 v[6:7], v[2:5], off offset:2048
	s_nop 1
	v_add_u32_e32 v2, 0x700, v137
	v_ashrrev_i32_e32 v3, 31, v2
	v_lshrrev_b32_e32 v3, 28, v3
	v_add_u32_e32 v3, v2, v3
	v_ashrrev_i32_e32 v4, 4, v3
	v_and_b32_e32 v3, -16, v3
	v_sub_u32_e32 v2, v2, v3
	v_bitop3_b32 v3, v4, v2, 15 bitop3:0x6c
	v_lshlrev_b32_e32 v5, 8, v4
	v_lshlrev_b32_e32 v2, 4, v2
	v_add3_u32 v8, s70, v5, v2
	v_lshlrev_b32_e32 v2, 3, v3
	v_mad_i64_i32 v[4:5], s[68:69], v4, s80, v[132:133]
	v_ashrrev_i32_e32 v3, 31, v2
	v_lshl_add_u64 v[6:7], v[2:3], 1, v[4:5]
	ds_read_b128 v[2:5], v8
	s_waitcnt lgkmcnt(0)
	global_store_dwordx4 v[6:7], v[2:5], off offset:2048
	s_barrier
	s_cbranch_scc1 .LBB0_870
